# GEMM epilogue row statistics: second-half partial-sum loads issued together with the first half (FF1, GATE, QLAT/CKV, KPE, SB/MB epilogues)
# baseline (speedup 1.0000x reference)
; #define LAS __attribute__((address_space(3)))
; DI float sum16(const float* p) { const f32x4 a = *(const f32x4*)p, b = *(const f32x4*)(p + 4), c = *(const f32x4*)(p + 8), d = *(const f32x4*)(p + 12); return (((a[0] + a[1]) + (a[2] + a[3])) + ((b[0] + b[1]) + (b[2] + b[3]))) + (((c[0] + c[1]) + (c[2] + c[3])) + ((d[0] + d[1]) + (d[2] + d[3]))); }
; DI float sum12(const float* p) { const f32x4 a = *(const f32x4*)p, b = *(const f32x4*)(p + 4), c = *(const f32x4*)(p + 8); return (((a[0] + a[1]) + (a[2] + a[3])) + ((b[0] + b[1]) + (b[2] + b[3]))) + ((c[0] + c[1]) + (c[2] + c[3])); }
;     template <int NS> DI void rowstat(float (&rs)[2][4], const float* parts, float inv_n, float mul, int rowbase_wave, LAS float* buf, int lane, int fr) const {
; #pragma unroll
;         for (int h = 0; h < 2; ++h) { const float* pp = parts + (size_t)(rowbase_wave + h * 128 + lane) * (NS == 4 ? 4 : 16);
;             const float sm = NS == 16 ? sum16(pp) : (NS == 12 ? sum12(pp) : sum4(pp)); buf[h * 64 + lane] = __builtin_amdgcn_rsqf(sm * inv_n + EPS) * mul; }
; #pragma unroll
;         for (int ai = 0; ai < 2; ++ai)
; #pragma unroll
;             for (int m = 0; m < 4; ++m) rs[ai][m] = buf[ai * 64 + m * 16 + fr];
;     }
;     DI void operator()(const f32x4 (&acc)[2][2][4][2], const Unit& u, int wr, int wc, int fr, int fq, int tid, LAS unsigned char* lds) const {
;     ...
;         case K_FF1: { EPI_CASE_BEGIN
;             bf16_t* dst = (bf16_t*)(ws + WS_H);
;             rowstat<16>(rs, ssq2, 1.f / 1024.f, 1.f, rbw, rsbuf, lane, fr);
;             f32x4 bv[2][2];
; #pragma unroll
;             for (int bj = 0; bj < 2; ++bj)
; #pragma unroll
;                 for (int n = 0; n < 2; ++n) bv[bj][n] = *(const f32x4*)(bias2 + bidx * 4096 + u.pn * 256 + lc0 + bj * 128 + n * 4);
; #pragma unroll
;             for (int ai = 0; ai < 2; ++ai)
; #pragma unroll
;                 for (int m = 0; m < 4; ++m) { const int row = row0 + ai * 128 + m * 16;
; #pragma unroll
;                     for (int bj = 0; bj < 2; ++bj) { f32x4 v0 = acc[ai][bj][m][0] * rs[ai][m] + bv[bj][0], v1 = acc[ai][bj][m][1] * rs[ai][m] + bv[bj][1];
; #pragma unroll
;                         for (int e = 0; e < 4; ++e) { const float t0 = fmaxf(v0[e], 0.f), t1 = fmaxf(v1[e], 0.f); v0[e] = t0 * t0; v1[e] = t1 * t1; }
;                         *(u32x4*)(dst + (size_t)row * 4096 + u.pn * 256 + lc0 + bj * 128) = PK8(v0, v1); } }
.LBB0_341:
	v_mov_b32_e32 v0, v229
	v_mov_b32_e32 v156, v230
	v_mov_b32_e32 v130, v231
	v_readlane_b32 s46, v252, 38
	v_lshl_add_u32 v152, v0, 3, s24
	v_and_b32_e32 v0, 63, v130
	v_readlane_b32 s47, v252, 39
	s_add_u32 s2, s50, s46
	v_lshlrev_b32_e32 v130, 3, v130
	v_or_b32_e32 v146, s54, v0
	s_addc_u32 s46, s51, s47
	v_and_b32_e32 v130, 0xfffffe00, v130
	v_readlane_b32 s47, v252, 1
	v_ashrrev_i32_e32 v147, 31, v146
	s_lshl_b32 s80, s14, 12
	v_add_u32_e32 v148, s47, v130
	v_lshlrev_b64 v[130:131], 6, v[146:147]
	v_lshl_add_u64 v[142:143], s[78:79], 0, v[130:131]
	global_load_dwordx4 v[130:133], v[142:143], off offset:48
	global_load_dwordx4 v[134:137], v[142:143], off offset:32
	global_load_dwordx4 v[138:141], v[142:143], off offset:16
	s_nop 0
	global_load_dwordx4 v[142:145], v[142:143], off
	v_add_u32_e32 v236, 0x80, v146
	v_ashrrev_i32_e32 v237, 31, v236
	v_lshlrev_b64 v[236:237], 6, v[236:237]
	v_lshl_add_u64 v[248:249], s[78:79], 0, v[236:237]
	global_load_dwordx4 v[236:239], v[248:249], off offset:48
	global_load_dwordx4 v[240:243], v[248:249], off offset:32
	global_load_dwordx4 v[244:247], v[248:249], off offset:16
	s_nop 0
	global_load_dwordx4 v[248:251], v[248:249], off
	s_ashr_i32 s81, s80, 31
	s_lshl_b64 s[80:81], s[80:81], 2
	s_add_u32 s2, s2, s80
	s_addc_u32 s71, s46, s81
	s_lshl_b32 s46, s38, 8
	s_ashr_i32 s47, s46, 31
	s_lshl_b64 s[80:81], s[46:47], 2
	s_add_u32 s80, s2, s80
	v_lshl_add_u32 v0, v0, 2, v148
	s_addc_u32 s81, s71, s81
	v_ashrrev_i32_e32 v153, 31, v152
	s_mov_b32 s2, 0xb00000
	s_waitcnt vmcnt(4)
	v_add_f32_e32 v130, v130, v131
	v_add_f32_e32 v134, v134, v135
	v_add_f32_e32 v138, v138, v139
	v_add_f32_e32 v142, v142, v143
	v_add_f32_e32 v143, v144, v145
	v_add_f32_e32 v139, v140, v141
	v_add_f32_e32 v135, v136, v137
	v_add_f32_e32 v131, v132, v133
	v_add_f32_e32 v142, v142, v143
	v_add_f32_e32 v138, v138, v139
	v_add_f32_e32 v134, v134, v135
	v_add_f32_e32 v130, v130, v131
	v_add_f32_e32 v138, v142, v138
	v_add_f32_e32 v130, v134, v130
	v_add_f32_e32 v130, v138, v130
	v_fmamk_f32 v130, v130, 0x3a800000, v212
	v_rsq_f32_e32 v147, v130
	s_waitcnt vmcnt(3)
	v_add_f32_e32 v236, v236, v237
	s_waitcnt vmcnt(2)
	v_add_f32_e32 v240, v240, v241
	s_waitcnt vmcnt(1)
	v_add_f32_e32 v244, v244, v245
	s_waitcnt vmcnt(0)
	v_add_f32_e32 v248, v248, v249
	v_add_f32_e32 v249, v250, v251
	v_add_f32_e32 v245, v246, v247
	v_add_f32_e32 v241, v242, v243
	v_add_f32_e32 v237, v238, v239
	v_add_f32_e32 v248, v248, v249
	v_add_f32_e32 v244, v244, v245
	v_add_f32_e32 v240, v240, v241
	v_add_f32_e32 v236, v236, v237
	v_add_f32_e32 v244, v248, v244
	v_add_f32_e32 v236, v240, v236
	v_add_f32_e32 v236, v244, v236
	v_fmamk_f32 v236, v236, 0x3a800000, v212
	v_rsq_f32_e32 v236, v236
	ds_write2st64_b32 v0, v147, v236 offset1:1
	v_lshl_add_u64 v[130:131], v[152:153], 2, s[80:81]
	s_mov_b64 s[80:81], 0xb00000
	v_lshl_add_u64 v[134:135], v[130:131], 0, s[80:81]
	v_add_co_u32_e32 v130, vcc, s2, v130
	v_lshl_add_u32 v0, v156, 2, v148
	s_nop 0
	v_addc_co_u32_e32 v131, vcc, 0, v131, vcc
	ds_read2_b32 v[154:155], v0 offset1:16
	ds_read2_b32 v[150:151], v0 offset0:32 offset1:48
	ds_read2_b32 v[148:149], v0 offset0:64 offset1:80
	ds_read2_b32 v[146:147], v0 offset0:96 offset1:112
	global_load_dwordx4 v[138:141], v[130:131], off
	global_load_dwordx4 v[142:145], v[134:135], off offset:16
	s_nop 0
	global_load_dwordx4 v[130:133], v[134:135], off offset:528
	s_nop 0
	global_load_dwordx4 v[134:137], v[134:135], off offset:512
	v_add_u32_e32 v156, s54, v156
	v_ashrrev_i32_e32 v157, 31, v156
	v_lshl_add_u64 v[152:153], v[152:153], 1, s[50:51]
	v_lshlrev_b64 v[156:157], 13, v[156:157]
	v_lshl_add_u64 v[152:153], v[152:153], 0, v[156:157]
	v_lshl_add_u64 v[152:153], s[46:47], 1, v[152:153]
	s_mov_b32 s2, 0xba00000
	s_mov_b64 s[46:47], 0xba00000
	s_waitcnt lgkmcnt(0)
	v_mov_b32_e32 v0, v155
	s_waitcnt vmcnt(3)
	v_pk_fma_f32 v[158:159], v[126:127], v[154:155], v[138:139] op_sel_hi:[1,0,1]
	s_waitcnt vmcnt(2)
	v_pk_fma_f32 v[162:163], v[122:123], v[154:155], v[142:143] op_sel_hi:[1,0,1]
	v_pk_fma_f32 v[156:157], v[128:129], v[154:155], v[140:141] op_sel_hi:[1,0,1]
	v_pk_fma_f32 v[160:161], v[124:125], v[154:155], v[144:145] op_sel_hi:[1,0,1]
	v_max_f32_e32 v158, 0, v158
	v_max_f32_e32 v162, 0, v162
	v_max_f32_e32 v159, 0, v159
	v_max_f32_e32 v163, 0, v163
	v_pk_mul_f32 v[158:159], v[158:159], v[158:159]
	v_pk_mul_f32 v[162:163], v[162:163], v[162:163]
	v_max_f32_e32 v156, 0, v156
	v_max_f32_e32 v160, 0, v160
	v_max_f32_e32 v157, 0, v157
	v_max_f32_e32 v161, 0, v161
	v_pk_mul_f32 v[164:165], v[156:157], v[156:157]
	v_pk_mul_f32 v[160:161], v[160:161], v[160:161]
	v_cvt_pk_bf16_f32 v156, v158, v159
	v_cvt_pk_bf16_f32 v158, v162, v163
	v_add_co_u32_e32 v162, vcc, s2, v152
	v_cvt_pk_bf16_f32 v157, v164, v165
	v_cvt_pk_bf16_f32 v159, v160, v161
	v_addc_co_u32_e32 v163, vcc, 0, v153, vcc
	global_store_dwordx4 v[162:163], v[156:159], off
	s_waitcnt vmcnt(2)
	v_pk_fma_f32 v[162:163], v[116:117], v[154:155], v[132:133] op_sel_hi:[1,0,1]
	v_pk_fma_f32 v[164:165], v[114:115], v[154:155], v[130:131] op_sel_hi:[1,0,1]
	s_waitcnt vmcnt(1)
; #define PK8(v0, v1) ((u32x4){pk2((v0)[0], (v0)[1]), pk2((v0)[2], (v0)[3]), pk2((v1)[0], (v1)[1]), pk2((v1)[2], (v1)[3])})
;     DI void operator()(const f32x4 (&acc)[2][2][4][2], const Unit& u, int wr, int wc, int fr, int fq, int tid, LAS unsigned char* lds) const {
;     ...
;             for (int ai = 0; ai < 2; ++ai)
; #pragma unroll
;                 for (int m = 0; m < 4; ++m) { const int row = row0 + ai * 128 + m * 16;
; #pragma unroll
;                     for (int bj = 0; bj < 2; ++bj) { f32x4 v0 = acc[ai][bj][m][0] * rs[ai][m] + bv[bj][0], v1 = acc[ai][bj][m][1] * rs[ai][m] + bv[bj][1];
; #pragma unroll
;                         for (int e = 0; e < 4; ++e) { const float t0 = fmaxf(v0[e], 0.f), t1 = fmaxf(v1[e], 0.f); v0[e] = t0 * t0; v1[e] = t1 * t1; }
;                         *(u32x4*)(dst + (size_t)row * 4096 + u.pn * 256 + lc0 + bj * 128) = PK8(v0, v1); } }
	v_pk_fma_f32 v[156:157], v[120:121], v[154:155], v[136:137] op_sel_hi:[1,0,1]
	v_pk_fma_f32 v[158:159], v[118:119], v[154:155], v[134:135] op_sel_hi:[1,0,1]
	v_max_f32_e32 v164, 0, v164
	v_max_f32_e32 v158, 0, v158
	v_max_f32_e32 v159, 0, v159
	v_max_f32_e32 v165, 0, v165
	v_max_f32_e32 v156, 0, v156
	v_max_f32_e32 v162, 0, v162
	v_max_f32_e32 v157, 0, v157
	v_max_f32_e32 v163, 0, v163
	v_pk_mul_f32 v[158:159], v[158:159], v[158:159]
	v_pk_mul_f32 v[164:165], v[164:165], v[164:165]
	v_pk_mul_f32 v[166:167], v[156:157], v[156:157]
	v_pk_mul_f32 v[162:163], v[162:163], v[162:163]
	v_lshl_add_u64 v[160:161], v[152:153], 0, s[46:47]
	v_cvt_pk_bf16_f32 v156, v158, v159
	v_cvt_pk_bf16_f32 v157, v166, v167
	v_cvt_pk_bf16_f32 v158, v164, v165
	v_cvt_pk_bf16_f32 v159, v162, v163
	global_store_dwordx4 v[160:161], v[156:159], off offset:256
	v_pk_fma_f32 v[160:161], v[106:107], v[0:1], v[142:143] op_sel_hi:[1,0,1]
	v_pk_fma_f32 v[154:155], v[112:113], v[0:1], v[140:141] op_sel_hi:[1,0,1]
	v_pk_fma_f32 v[156:157], v[110:111], v[0:1], v[138:139] op_sel_hi:[1,0,1]
	v_pk_fma_f32 v[158:159], v[108:109], v[0:1], v[144:145] op_sel_hi:[1,0,1]
	v_max_f32_e32 v156, 0, v156
	v_max_f32_e32 v160, 0, v160
	v_max_f32_e32 v157, 0, v157
	v_max_f32_e32 v161, 0, v161
	v_pk_mul_f32 v[156:157], v[156:157], v[156:157]
	v_pk_mul_f32 v[160:161], v[160:161], v[160:161]
	v_max_f32_e32 v154, 0, v154
	v_max_f32_e32 v158, 0, v158
	v_max_f32_e32 v155, 0, v155
	v_max_f32_e32 v159, 0, v159
	s_mov_b32 s2, 0xba20000
	v_pk_mul_f32 v[162:163], v[154:155], v[154:155]
	v_pk_mul_f32 v[158:159], v[158:159], v[158:159]
	v_cvt_pk_bf16_f32 v154, v156, v157
	v_cvt_pk_bf16_f32 v156, v160, v161
	v_add_co_u32_e32 v160, vcc, s2, v152
	v_cvt_pk_bf16_f32 v155, v162, v163
	v_cvt_pk_bf16_f32 v157, v158, v159
	v_addc_co_u32_e32 v161, vcc, 0, v153, vcc
	global_store_dwordx4 v[160:161], v[154:157], off
	v_pk_fma_f32 v[160:161], v[100:101], v[0:1], v[132:133] op_sel_hi:[1,0,1]
	v_pk_fma_f32 v[162:163], v[98:99], v[0:1], v[130:131] op_sel_hi:[1,0,1]
	v_pk_fma_f32 v[154:155], v[104:105], v[0:1], v[136:137] op_sel_hi:[1,0,1]
	v_pk_fma_f32 v[156:157], v[102:103], v[0:1], v[134:135] op_sel_hi:[1,0,1]
	v_max_f32_e32 v162, 0, v162
	v_max_f32_e32 v156, 0, v156
	v_max_f32_e32 v157, 0, v157
	v_max_f32_e32 v163, 0, v163
	v_max_f32_e32 v154, 0, v154
	v_max_f32_e32 v160, 0, v160
	v_max_f32_e32 v155, 0, v155
	v_max_f32_e32 v161, 0, v161
	s_mov_b64 s[46:47], 0xba20000
	v_pk_mul_f32 v[156:157], v[156:157], v[156:157]
	v_pk_mul_f32 v[162:163], v[162:163], v[162:163]
	v_pk_mul_f32 v[164:165], v[154:155], v[154:155]
	v_pk_mul_f32 v[160:161], v[160:161], v[160:161]
	v_lshl_add_u64 v[158:159], v[152:153], 0, s[46:47]
	v_cvt_pk_bf16_f32 v154, v156, v157
	v_cvt_pk_bf16_f32 v155, v164, v165
	v_cvt_pk_bf16_f32 v156, v162, v163
	v_cvt_pk_bf16_f32 v157, v160, v161
	global_store_dwordx4 v[158:159], v[154:157], off offset:256
	v_pk_fma_f32 v[160:161], v[90:91], v[150:151], v[142:143] op_sel_hi:[1,0,1]
	v_pk_fma_f32 v[158:159], v[92:93], v[150:151], v[144:145] op_sel_hi:[1,0,1]
	v_pk_fma_f32 v[156:157], v[94:95], v[150:151], v[138:139] op_sel_hi:[1,0,1]
	v_pk_fma_f32 v[154:155], v[96:97], v[150:151], v[140:141] op_sel_hi:[1,0,1]
	v_max_f32_e32 v156, 0, v156
	v_max_f32_e32 v160, 0, v160
	v_max_f32_e32 v157, 0, v157
	v_max_f32_e32 v161, 0, v161
	v_pk_mul_f32 v[156:157], v[156:157], v[156:157]
	v_pk_mul_f32 v[160:161], v[160:161], v[160:161]
	v_max_f32_e32 v154, 0, v154
	v_max_f32_e32 v158, 0, v158
	v_max_f32_e32 v155, 0, v155
	v_max_f32_e32 v159, 0, v159
	s_mov_b32 s2, 0xba40000
	v_pk_mul_f32 v[162:163], v[154:155], v[154:155]
	v_pk_mul_f32 v[158:159], v[158:159], v[158:159]
	v_cvt_pk_bf16_f32 v154, v156, v157
	v_cvt_pk_bf16_f32 v156, v160, v161
	v_add_co_u32_e32 v160, vcc, s2, v152
	v_cvt_pk_bf16_f32 v155, v162, v163
	v_cvt_pk_bf16_f32 v157, v158, v159
	v_addc_co_u32_e32 v161, vcc, 0, v153, vcc
	global_store_dwordx4 v[160:161], v[154:157], off
	v_pk_fma_f32 v[160:161], v[84:85], v[150:151], v[132:133] op_sel_hi:[1,0,1]
	v_pk_fma_f32 v[162:163], v[82:83], v[150:151], v[130:131] op_sel_hi:[1,0,1]
	v_pk_fma_f32 v[154:155], v[88:89], v[150:151], v[136:137] op_sel_hi:[1,0,1]
	v_pk_fma_f32 v[156:157], v[86:87], v[150:151], v[134:135] op_sel_hi:[1,0,1]
	v_max_f32_e32 v162, 0, v162
	v_max_f32_e32 v156, 0, v156
	v_max_f32_e32 v157, 0, v157
	v_max_f32_e32 v163, 0, v163
	v_max_f32_e32 v154, 0, v154
	v_max_f32_e32 v160, 0, v160
	v_max_f32_e32 v155, 0, v155
	v_max_f32_e32 v161, 0, v161
	s_mov_b64 s[46:47], 0xba40000
	v_pk_mul_f32 v[156:157], v[156:157], v[156:157]
	v_pk_mul_f32 v[162:163], v[162:163], v[162:163]
	v_pk_mul_f32 v[164:165], v[154:155], v[154:155]
	v_pk_mul_f32 v[160:161], v[160:161], v[160:161]
	v_lshl_add_u64 v[158:159], v[152:153], 0, s[46:47]
	v_cvt_pk_bf16_f32 v154, v156, v157
	v_cvt_pk_bf16_f32 v155, v164, v165
	v_cvt_pk_bf16_f32 v156, v162, v163
	v_cvt_pk_bf16_f32 v157, v160, v161
	v_mov_b32_e32 v0, v151
	global_store_dwordx4 v[158:159], v[154:157], off offset:256
	v_pk_fma_f32 v[158:159], v[74:75], v[0:1], v[142:143] op_sel_hi:[1,0,1]
	v_pk_fma_f32 v[150:151], v[80:81], v[0:1], v[140:141] op_sel_hi:[1,0,1]
	v_pk_fma_f32 v[154:155], v[78:79], v[0:1], v[138:139] op_sel_hi:[1,0,1]
	v_pk_fma_f32 v[156:157], v[76:77], v[0:1], v[144:145] op_sel_hi:[1,0,1]
	v_max_f32_e32 v158, 0, v158
	v_max_f32_e32 v159, 0, v159
	v_max_f32_e32 v154, 0, v154
	v_max_f32_e32 v155, 0, v155
	v_pk_mul_f32 v[158:159], v[158:159], v[158:159]
	v_max_f32_e32 v150, 0, v150
	v_max_f32_e32 v156, 0, v156
	v_max_f32_e32 v151, 0, v151
	v_max_f32_e32 v157, 0, v157
	s_mov_b32 s2, 0xba60000
	v_pk_mul_f32 v[154:155], v[154:155], v[154:155]
; #define PK8(v0, v1) ((u32x4){pk2((v0)[0], (v0)[1]), pk2((v0)[2], (v0)[3]), pk2((v1)[0], (v1)[1]), pk2((v1)[2], (v1)[3])})
;     DI void operator()(const f32x4 (&acc)[2][2][4][2], const Unit& u, int wr, int wc, int fr, int fq, int tid, LAS unsigned char* lds) const {
;     ...
;             for (int ai = 0; ai < 2; ++ai)
; #pragma unroll
;                 for (int m = 0; m < 4; ++m) { const int row = row0 + ai * 128 + m * 16;
; #pragma unroll
;                     for (int bj = 0; bj < 2; ++bj) { f32x4 v0 = acc[ai][bj][m][0] * rs[ai][m] + bv[bj][0], v1 = acc[ai][bj][m][1] * rs[ai][m] + bv[bj][1];
; #pragma unroll
;                         for (int e = 0; e < 4; ++e) { const float t0 = fmaxf(v0[e], 0.f), t1 = fmaxf(v1[e], 0.f); v0[e] = t0 * t0; v1[e] = t1 * t1; }
;                         *(u32x4*)(dst + (size_t)row * 4096 + u.pn * 256 + lc0 + bj * 128) = PK8(v0, v1); } }
	v_pk_mul_f32 v[150:151], v[150:151], v[150:151]
	v_pk_mul_f32 v[160:161], v[156:157], v[156:157]
	v_cvt_pk_bf16_f32 v156, v158, v159
	v_add_co_u32_e32 v158, vcc, s2, v152
	v_cvt_pk_bf16_f32 v154, v154, v155
	v_cvt_pk_bf16_f32 v155, v150, v151
	v_cvt_pk_bf16_f32 v157, v160, v161
	v_addc_co_u32_e32 v159, vcc, 0, v153, vcc
	global_store_dwordx4 v[158:159], v[154:157], off
	v_pk_fma_f32 v[158:159], v[68:69], v[0:1], v[132:133] op_sel_hi:[1,0,1]
	v_pk_fma_f32 v[160:161], v[66:67], v[0:1], v[130:131] op_sel_hi:[1,0,1]
	v_pk_fma_f32 v[154:155], v[72:73], v[0:1], v[136:137] op_sel_hi:[1,0,1]
	v_pk_fma_f32 v[156:157], v[70:71], v[0:1], v[134:135] op_sel_hi:[1,0,1]
	v_max_f32_e32 v160, 0, v160
	v_max_f32_e32 v156, 0, v156
	v_max_f32_e32 v157, 0, v157
	v_max_f32_e32 v161, 0, v161
	v_max_f32_e32 v154, 0, v154
	v_max_f32_e32 v158, 0, v158
	v_max_f32_e32 v155, 0, v155
	v_max_f32_e32 v159, 0, v159
	s_mov_b64 s[46:47], 0xba60000
	v_pk_mul_f32 v[156:157], v[156:157], v[156:157]
	v_pk_mul_f32 v[160:161], v[160:161], v[160:161]
	v_pk_mul_f32 v[162:163], v[154:155], v[154:155]
	v_pk_mul_f32 v[158:159], v[158:159], v[158:159]
	v_lshl_add_u64 v[150:151], v[152:153], 0, s[46:47]
	v_cvt_pk_bf16_f32 v154, v156, v157
	v_cvt_pk_bf16_f32 v155, v162, v163
	v_cvt_pk_bf16_f32 v156, v160, v161
	v_cvt_pk_bf16_f32 v157, v158, v159
	v_pk_fma_f32 v[158:159], v[58:59], v[148:149], v[142:143] op_sel_hi:[1,0,1]
	global_store_dwordx4 v[150:151], v[154:157], off offset:256
	v_pk_fma_f32 v[150:151], v[64:65], v[148:149], v[140:141] op_sel_hi:[1,0,1]
	v_max_f32_e32 v158, 0, v158
	v_pk_fma_f32 v[154:155], v[62:63], v[148:149], v[138:139] op_sel_hi:[1,0,1]
	v_pk_fma_f32 v[156:157], v[60:61], v[148:149], v[144:145] op_sel_hi:[1,0,1]
	v_max_f32_e32 v159, 0, v159
	v_max_f32_e32 v154, 0, v154
	v_max_f32_e32 v155, 0, v155
	v_pk_mul_f32 v[158:159], v[158:159], v[158:159]
	v_max_f32_e32 v150, 0, v150
	v_max_f32_e32 v156, 0, v156
	v_max_f32_e32 v151, 0, v151
	v_max_f32_e32 v157, 0, v157
	s_mov_b32 s2, 0xbb00000
	v_pk_mul_f32 v[154:155], v[154:155], v[154:155]
	v_pk_mul_f32 v[150:151], v[150:151], v[150:151]
	v_pk_mul_f32 v[160:161], v[156:157], v[156:157]
	v_cvt_pk_bf16_f32 v156, v158, v159
	v_add_co_u32_e32 v158, vcc, s2, v152
	v_cvt_pk_bf16_f32 v154, v154, v155
	v_cvt_pk_bf16_f32 v155, v150, v151
	v_cvt_pk_bf16_f32 v157, v160, v161
	v_addc_co_u32_e32 v159, vcc, 0, v153, vcc
	global_store_dwordx4 v[158:159], v[154:157], off
	v_pk_fma_f32 v[158:159], v[52:53], v[148:149], v[132:133] op_sel_hi:[1,0,1]
	v_pk_fma_f32 v[160:161], v[50:51], v[148:149], v[130:131] op_sel_hi:[1,0,1]
	v_pk_fma_f32 v[154:155], v[56:57], v[148:149], v[136:137] op_sel_hi:[1,0,1]
	v_pk_fma_f32 v[156:157], v[54:55], v[148:149], v[134:135] op_sel_hi:[1,0,1]
	v_max_f32_e32 v160, 0, v160
	v_max_f32_e32 v156, 0, v156
	v_max_f32_e32 v157, 0, v157
	v_max_f32_e32 v161, 0, v161
	v_max_f32_e32 v154, 0, v154
	v_max_f32_e32 v158, 0, v158
	v_max_f32_e32 v155, 0, v155
	v_max_f32_e32 v159, 0, v159
	s_mov_b64 s[46:47], 0xbb00000
	v_pk_mul_f32 v[156:157], v[156:157], v[156:157]
	v_pk_mul_f32 v[160:161], v[160:161], v[160:161]
	v_pk_mul_f32 v[162:163], v[154:155], v[154:155]
	v_pk_mul_f32 v[158:159], v[158:159], v[158:159]
	v_lshl_add_u64 v[150:151], v[152:153], 0, s[46:47]
	v_cvt_pk_bf16_f32 v154, v156, v157
	v_cvt_pk_bf16_f32 v155, v162, v163
	v_cvt_pk_bf16_f32 v156, v160, v161
	v_cvt_pk_bf16_f32 v157, v158, v159
	v_mov_b32_e32 v0, v149
	global_store_dwordx4 v[150:151], v[154:157], off offset:256
	v_pk_fma_f32 v[150:151], v[46:47], v[0:1], v[138:139] op_sel_hi:[1,0,1]
	v_pk_fma_f32 v[148:149], v[48:49], v[0:1], v[140:141] op_sel_hi:[1,0,1]
	v_pk_fma_f32 v[156:157], v[42:43], v[0:1], v[142:143] op_sel_hi:[1,0,1]
	v_pk_fma_f32 v[154:155], v[44:45], v[0:1], v[144:145] op_sel_hi:[1,0,1]
	v_max_f32_e32 v150, 0, v150
	v_max_f32_e32 v156, 0, v156
	v_max_f32_e32 v151, 0, v151
	v_max_f32_e32 v157, 0, v157
	v_pk_mul_f32 v[150:151], v[150:151], v[150:151]
	v_pk_mul_f32 v[156:157], v[156:157], v[156:157]
	v_max_f32_e32 v148, 0, v148
	v_max_f32_e32 v154, 0, v154
	v_max_f32_e32 v149, 0, v149
	v_max_f32_e32 v155, 0, v155
	s_mov_b32 s2, 0xbb20000
	v_pk_mul_f32 v[158:159], v[148:149], v[148:149]
	v_pk_mul_f32 v[154:155], v[154:155], v[154:155]
	v_cvt_pk_bf16_f32 v148, v150, v151
	v_cvt_pk_bf16_f32 v150, v156, v157
	v_add_co_u32_e32 v156, vcc, s2, v152
	v_cvt_pk_bf16_f32 v149, v158, v159
	v_cvt_pk_bf16_f32 v151, v154, v155
	v_addc_co_u32_e32 v157, vcc, 0, v153, vcc
	global_store_dwordx4 v[156:157], v[148:151], off
	v_pk_fma_f32 v[156:157], v[36:37], v[0:1], v[132:133] op_sel_hi:[1,0,1]
	v_pk_fma_f32 v[158:159], v[34:35], v[0:1], v[130:131] op_sel_hi:[1,0,1]
	v_pk_fma_f32 v[148:149], v[40:41], v[0:1], v[136:137] op_sel_hi:[1,0,1]
	v_pk_fma_f32 v[150:151], v[38:39], v[0:1], v[134:135] op_sel_hi:[1,0,1]
	v_max_f32_e32 v158, 0, v158
; #define PK8(v0, v1) ((u32x4){pk2((v0)[0], (v0)[1]), pk2((v0)[2], (v0)[3]), pk2((v1)[0], (v1)[1]), pk2((v1)[2], (v1)[3])})
;     DI void operator()(const f32x4 (&acc)[2][2][4][2], const Unit& u, int wr, int wc, int fr, int fq, int tid, LAS unsigned char* lds) const {
;     ...
;             for (int ai = 0; ai < 2; ++ai)
; #pragma unroll
;                 for (int m = 0; m < 4; ++m) { const int row = row0 + ai * 128 + m * 16;
; #pragma unroll
;                     for (int bj = 0; bj < 2; ++bj) { f32x4 v0 = acc[ai][bj][m][0] * rs[ai][m] + bv[bj][0], v1 = acc[ai][bj][m][1] * rs[ai][m] + bv[bj][1];
; #pragma unroll
;                         for (int e = 0; e < 4; ++e) { const float t0 = fmaxf(v0[e], 0.f), t1 = fmaxf(v1[e], 0.f); v0[e] = t0 * t0; v1[e] = t1 * t1; }
;                         *(u32x4*)(dst + (size_t)row * 4096 + u.pn * 256 + lc0 + bj * 128) = PK8(v0, v1); } }
	v_max_f32_e32 v150, 0, v150
	v_max_f32_e32 v151, 0, v151
	v_max_f32_e32 v159, 0, v159
	v_max_f32_e32 v148, 0, v148
	v_max_f32_e32 v156, 0, v156
	v_max_f32_e32 v149, 0, v149
	v_max_f32_e32 v157, 0, v157
	s_mov_b64 s[46:47], 0xbb20000
	v_pk_mul_f32 v[150:151], v[150:151], v[150:151]
	v_pk_mul_f32 v[158:159], v[158:159], v[158:159]
	v_pk_mul_f32 v[160:161], v[148:149], v[148:149]
	v_pk_mul_f32 v[156:157], v[156:157], v[156:157]
	v_lshl_add_u64 v[154:155], v[152:153], 0, s[46:47]
	v_cvt_pk_bf16_f32 v148, v150, v151
	v_cvt_pk_bf16_f32 v149, v160, v161
	v_cvt_pk_bf16_f32 v150, v158, v159
	v_cvt_pk_bf16_f32 v151, v156, v157
	global_store_dwordx4 v[154:155], v[148:151], off offset:256
	v_pk_fma_f32 v[156:157], v[26:27], v[146:147], v[142:143] op_sel_hi:[1,0,1]
	v_mov_b32_e32 v0, v147
	v_pk_fma_f32 v[150:151], v[30:31], v[146:147], v[138:139] op_sel_hi:[1,0,1]
	v_pk_fma_f32 v[148:149], v[32:33], v[146:147], v[140:141] op_sel_hi:[1,0,1]
	v_max_f32_e32 v150, 0, v150
	v_max_f32_e32 v156, 0, v156
	v_max_f32_e32 v151, 0, v151
	v_max_f32_e32 v157, 0, v157
	v_pk_fma_f32 v[154:155], v[28:29], v[146:147], v[144:145] op_sel_hi:[1,0,1]
	v_pk_mul_f32 v[150:151], v[150:151], v[150:151]
	v_pk_mul_f32 v[156:157], v[156:157], v[156:157]
	v_max_f32_e32 v148, 0, v148
	v_max_f32_e32 v149, 0, v149
	s_mov_b32 s2, 0xbb40000
	v_pk_fma_f32 v[140:141], v[16:17], v[0:1], v[140:141] op_sel_hi:[1,0,1]
	v_pk_fma_f32 v[138:139], v[14:15], v[0:1], v[138:139] op_sel_hi:[1,0,1]
	v_pk_fma_f32 v[144:145], v[12:13], v[0:1], v[144:145] op_sel_hi:[1,0,1]
	v_max_f32_e32 v154, 0, v154
	v_max_f32_e32 v155, 0, v155
	v_pk_mul_f32 v[158:159], v[148:149], v[148:149]
	v_cvt_pk_bf16_f32 v148, v150, v151
	v_cvt_pk_bf16_f32 v150, v156, v157
	v_add_co_u32_e32 v156, vcc, s2, v152
	v_pk_fma_f32 v[142:143], v[10:11], v[0:1], v[142:143] op_sel_hi:[1,0,1]
	v_max_f32_e32 v138, 0, v138
	v_max_f32_e32 v139, 0, v139
	v_max_f32_e32 v140, 0, v140
	v_max_f32_e32 v144, 0, v144
	v_max_f32_e32 v141, 0, v141
	v_max_f32_e32 v145, 0, v145
	v_pk_mul_f32 v[154:155], v[154:155], v[154:155]
	v_addc_co_u32_e32 v157, vcc, 0, v153, vcc
	v_max_f32_e32 v142, 0, v142
	v_max_f32_e32 v143, 0, v143
	v_pk_mul_f32 v[138:139], v[138:139], v[138:139]
	v_pk_mul_f32 v[140:141], v[140:141], v[140:141]
	v_pk_mul_f32 v[144:145], v[144:145], v[144:145]
	s_mov_b32 s2, 0xbb60000
	v_cvt_pk_bf16_f32 v149, v158, v159
	v_cvt_pk_bf16_f32 v151, v154, v155
	v_pk_fma_f32 v[158:159], v[18:19], v[146:147], v[130:131] op_sel_hi:[1,0,1]
	v_pk_mul_f32 v[142:143], v[142:143], v[142:143]
	v_cvt_pk_bf16_f32 v138, v138, v139
	v_cvt_pk_bf16_f32 v139, v140, v141
	v_cvt_pk_bf16_f32 v141, v144, v145
	v_add_co_u32_e32 v144, vcc, s2, v152
	v_pk_fma_f32 v[130:131], v[2:3], v[0:1], v[130:131] op_sel_hi:[1,0,1]
	global_store_dwordx4 v[156:157], v[148:151], off
	v_pk_fma_f32 v[156:157], v[20:21], v[146:147], v[132:133] op_sel_hi:[1,0,1]
	v_cvt_pk_bf16_f32 v140, v142, v143
	v_pk_fma_f32 v[148:149], v[24:25], v[146:147], v[136:137] op_sel_hi:[1,0,1]
	v_pk_fma_f32 v[150:151], v[22:23], v[146:147], v[134:135] op_sel_hi:[1,0,1]
	v_addc_co_u32_e32 v145, vcc, 0, v153, vcc
	v_pk_fma_f32 v[136:137], v[8:9], v[0:1], v[136:137] op_sel_hi:[1,0,1]
	v_pk_fma_f32 v[134:135], v[6:7], v[0:1], v[134:135] op_sel_hi:[1,0,1]
	v_pk_fma_f32 v[132:133], v[4:5], v[0:1], v[132:133] op_sel_hi:[1,0,1]
	v_max_f32_e32 v130, 0, v130
	v_max_f32_e32 v131, 0, v131
	s_mov_b64 s[46:47], 0xbb40000
	v_max_f32_e32 v150, 0, v150
	v_max_f32_e32 v158, 0, v158
	v_max_f32_e32 v151, 0, v151
	v_max_f32_e32 v159, 0, v159
	v_max_f32_e32 v148, 0, v148
	v_max_f32_e32 v156, 0, v156
	v_max_f32_e32 v149, 0, v149
	v_max_f32_e32 v157, 0, v157
	global_store_dwordx4 v[144:145], v[138:141], off
	v_max_f32_e32 v134, 0, v134
	v_max_f32_e32 v135, 0, v135
	v_pk_mul_f32 v[138:139], v[130:131], v[130:131]
	v_max_f32_e32 v130, 0, v136
	v_max_f32_e32 v132, 0, v132
	v_max_f32_e32 v131, 0, v137
	v_max_f32_e32 v133, 0, v133
	v_lshl_add_u64 v[154:155], v[152:153], 0, s[46:47]
	v_pk_mul_f32 v[150:151], v[150:151], v[150:151]
	v_pk_mul_f32 v[158:159], v[158:159], v[158:159]
	v_pk_mul_f32 v[160:161], v[148:149], v[148:149]
	v_pk_mul_f32 v[156:157], v[156:157], v[156:157]
	s_mov_b64 s[46:47], 0xbb60000
	v_pk_mul_f32 v[134:135], v[134:135], v[134:135]
	v_pk_mul_f32 v[136:137], v[130:131], v[130:131]
	v_pk_mul_f32 v[140:141], v[132:133], v[132:133]
	v_cvt_pk_bf16_f32 v148, v150, v151
	v_cvt_pk_bf16_f32 v149, v160, v161
	v_cvt_pk_bf16_f32 v150, v158, v159
	v_cvt_pk_bf16_f32 v151, v156, v157
	v_lshl_add_u64 v[142:143], v[152:153], 0, s[46:47]
	v_cvt_pk_bf16_f32 v130, v134, v135
	v_cvt_pk_bf16_f32 v131, v136, v137
	v_cvt_pk_bf16_f32 v132, v138, v139
	v_cvt_pk_bf16_f32 v133, v140, v141
	global_store_dwordx4 v[154:155], v[148:151], off offset:256
	global_store_dwordx4 v[142:143], v[130:133], off offset:256

; #define LAS __attribute__((address_space(3)))
; DI float sigmoidf_(float x) { return __builtin_amdgcn_rcpf(1.f + fast_exp(-x)); }
; DI float sum16(const float* p) { const f32x4 a = *(const f32x4*)p, b = *(const f32x4*)(p + 4), c = *(const f32x4*)(p + 8), d = *(const f32x4*)(p + 12); return (((a[0] + a[1]) + (a[2] + a[3])) + ((b[0] + b[1]) + (b[2] + b[3]))) + (((c[0] + c[1]) + (c[2] + c[3])) + ((d[0] + d[1]) + (d[2] + d[3]))); }
; DI float sum4(const float* p) { const f32x4 a = *(const f32x4*)p; return (a[0] + a[1]) + (a[2] + a[3]); }
;     template <int NS> DI void rowstat(float (&rs)[2][4], const float* parts, float inv_n, float mul, int rowbase_wave, LAS float* buf, int lane, int fr) const {
; #pragma unroll
;         for (int h = 0; h < 2; ++h) { const float* pp = parts + (size_t)(rowbase_wave + h * 128 + lane) * (NS == 4 ? 4 : 16);
;             const float sm = NS == 16 ? sum16(pp) : (NS == 12 ? sum12(pp) : sum4(pp)); buf[h * 64 + lane] = __builtin_amdgcn_rsqf(sm * inv_n + EPS) * mul; }
; #pragma unroll
;         for (int ai = 0; ai < 2; ++ai)
; #pragma unroll
;             for (int m = 0; m < 4; ++m) rs[ai][m] = buf[ai * 64 + m * 16 + fr];
;     }
;     DI void operator()(const f32x4 (&acc)[2][2][4][2], const Unit& u, int wr, int wc, int fr, int fq, int tid, LAS unsigned char* lds) const {
;     ...
;         case K_GATE: { EPI_CASE_BEGIN
;             u32x4* st = (u32x4*)(ws + WS_STASH + (size_t)blockIdx.x * 131072) + tid;
;             const int gcol = (int)((u.B - (const char*)(ws + W_IN)) >> 11) + lc0;
;             rowstat<16>(rs, ssq1, 1.f / 1024.f, 1.f, rbw, rsbuf, lane, fr);
;             f32x4 bv[2][2];
; #pragma unroll
;             for (int bj = 0; bj < 2; ++bj)
; #pragma unroll
;                 for (int n = 0; n < 2; ++n) bv[bj][n] = *(const f32x4*)(bias1 + bidx * NWIN + gcol + bj * 128 + n * 4);
; #pragma unroll
;             for (int ai = 0; ai < 2; ++ai)
; #pragma unroll
;                 for (int m = 0; m < 4; ++m)
; #pragma unroll
;                     for (int bj = 0; bj < 2; ++bj) { f32x4 g0, g1;
;                         const f32x4 a0 = acc[ai][bj][m][0] * rs[ai][m] + bv[bj][0], a1 = acc[ai][bj][m][1] * rs[ai][m] + bv[bj][1];
; #pragma unroll
;                         for (int e = 0; e < 4; ++e) { g0[e] = sigmoidf_(a0[e]); g1[e] = sigmoidf_(a1[e]); }
;                         st[((ai * 4 + m) * 2 + bj) * 512] = PK8(g0, g1); }
.LBB0_500:
	s_and_b64 vcc, exec, s[42:43]
	s_cbranch_vccz .LBB0_502
	v_mov_b32_e32 v148, v231
	s_waitcnt lgkmcnt(0)
	v_mov_b32_e32 v0, v229
	v_mov_b32_e32 v131, v230
	v_readlane_b32 s2, v252, 1
	v_lshlrev_b32_e32 v130, 3, v148
	v_and_b32_e32 v130, 0xfffffe00, v130
	v_add_u32_e32 v152, s2, v130
	s_add_u32 s2, s50, 0x1000000
	s_addc_u32 s43, s51, 0
	s_sub_u32 s42, s66, s2
	v_and_b32_e32 v132, 63, v148
	s_subb_u32 s43, s67, s43
	s_lshr_b64 s[42:43], s[42:43], 11
	v_or_b32_e32 v150, s54, v132
	s_add_i32 s2, s24, s42
	v_ashrrev_i32_e32 v151, 31, v150
	v_lshl_add_u32 v130, v0, 3, s2
	v_lshl_add_u32 v0, v132, 2, v152
	v_lshlrev_b64 v[132:133], 6, v[150:151]
	v_lshl_add_u64 v[144:145], s[18:19], 0, v[132:133]
	global_load_dwordx4 v[132:135], v[144:145], off offset:48
	global_load_dwordx4 v[136:139], v[144:145], off offset:32
	global_load_dwordx4 v[140:143], v[144:145], off offset:16
	s_nop 0
	global_load_dwordx4 v[144:147], v[144:145], off
	v_add_u32_e32 v236, 0x80, v150
	v_ashrrev_i32_e32 v237, 31, v236
	v_lshlrev_b64 v[236:237], 6, v[236:237]
	v_lshl_add_u64 v[248:249], s[18:19], 0, v[236:237]
	global_load_dwordx4 v[236:239], v[248:249], off offset:48
	global_load_dwordx4 v[240:243], v[248:249], off offset:32
	global_load_dwordx4 v[244:247], v[248:249], off offset:16
	s_nop 0
	global_load_dwordx4 v[248:251], v[248:249], off
	s_mul_i32 s42, s14, 0x1d00
	s_ashr_i32 s43, s42, 31
	s_lshl_b64 s[42:43], s[42:43], 2
	s_add_u32 s42, s57, s42
	s_addc_u32 s43, s86, s43
	v_ashrrev_i32_e32 v149, 31, v148
	s_mov_b32 s2, 0x17a00000
	s_waitcnt vmcnt(4)
	v_add_f32_e32 v132, v132, v133
	v_add_f32_e32 v136, v136, v137
	v_add_f32_e32 v140, v140, v141
	v_add_f32_e32 v144, v144, v145
	v_add_f32_e32 v145, v146, v147
	v_add_f32_e32 v141, v142, v143
	v_add_f32_e32 v137, v138, v139
	v_add_f32_e32 v133, v134, v135
	v_add_f32_e32 v144, v144, v145
	v_add_f32_e32 v140, v140, v141
	v_add_f32_e32 v136, v136, v137
	v_add_f32_e32 v132, v132, v133
	v_add_f32_e32 v140, v144, v140
	v_add_f32_e32 v132, v136, v132
	v_add_f32_e32 v132, v140, v132
	v_fmamk_f32 v132, v132, 0x3a800000, v212
	v_rsq_f32_e32 v151, v132
	s_waitcnt vmcnt(3)
	v_add_f32_e32 v236, v236, v237
	s_waitcnt vmcnt(2)
	v_add_f32_e32 v240, v240, v241
	s_waitcnt vmcnt(1)
	v_add_f32_e32 v244, v244, v245
	s_waitcnt vmcnt(0)
	v_add_f32_e32 v248, v248, v249
	v_add_f32_e32 v249, v250, v251
	v_add_f32_e32 v245, v246, v247
	v_add_f32_e32 v241, v242, v243
	v_add_f32_e32 v237, v238, v239
	v_add_f32_e32 v248, v248, v249
	v_add_f32_e32 v244, v244, v245
	v_add_f32_e32 v240, v240, v241
	v_add_f32_e32 v236, v236, v237
	v_add_f32_e32 v244, v248, v244
	v_add_f32_e32 v236, v240, v236
	v_add_f32_e32 v236, v244, v236
	v_fmamk_f32 v236, v236, 0x3a800000, v212
	v_rsq_f32_e32 v236, v236
	ds_write2st64_b32 v0, v151, v236 offset1:1
	v_lshl_add_u32 v0, v131, 2, v152
	v_ashrrev_i32_e32 v131, 31, v130
	v_lshl_add_u64 v[134:135], v[130:131], 2, s[42:43]
	ds_read2_b32 v[154:155], v0 offset1:16
	ds_read2_b32 v[152:153], v0 offset0:32 offset1:48
	ds_read2_b32 v[150:151], v0 offset0:64 offset1:80
	ds_read2_b32 v[146:147], v0 offset0:96 offset1:112
	global_load_dwordx4 v[138:141], v[134:135], off offset:16
	global_load_dwordx4 v[142:145], v[134:135], off
	global_load_dwordx4 v[130:133], v[134:135], off offset:528
	s_nop 0
	global_load_dwordx4 v[134:137], v[134:135], off offset:512
	v_readlane_b32 s42, v254, 21
	v_readlane_b32 s43, v254, 22
	s_add_u32 s42, s50, s42
	s_addc_u32 s43, s51, s43
	v_lshl_add_u64 v[148:149], v[148:149], 4, s[42:43]
	s_waitcnt vmcnt(3) lgkmcnt(3)
	v_fma_f32 v156, v122, v154, v138
	v_fma_f32 v157, v123, v154, v139
	v_mul_f32_e32 v156, 0xbfb8aa3b, v156
	v_mul_f32_e32 v157, 0xbfb8aa3b, v157
	v_exp_f32_e32 v156, v156
	v_exp_f32_e32 v157, v157
	v_fma_f32 v160, v124, v154, v140
	v_fma_f32 v162, v125, v154, v141
	v_add_f32_e32 v156, 1.0, v156
	v_add_f32_e32 v157, 1.0, v157
	s_waitcnt vmcnt(2)
	v_fma_f32 v0, v126, v154, v142
	v_rcp_f32_e32 v158, v156
	v_fma_f32 v156, v127, v154, v143
	v_rcp_f32_e32 v159, v157
	v_fma_f32 v157, v128, v154, v144
	v_mul_f32_e32 v160, 0xbfb8aa3b, v160
	v_fma_f32 v161, v129, v154, v145
	v_mul_f32_e32 v162, 0xbfb8aa3b, v162
	v_mul_f32_e32 v0, 0xbfb8aa3b, v0
	v_mul_f32_e32 v156, 0xbfb8aa3b, v156
	v_mul_f32_e32 v157, 0xbfb8aa3b, v157
	v_exp_f32_e32 v160, v160
	v_mul_f32_e32 v161, 0xbfb8aa3b, v161
	v_exp_f32_e32 v162, v162
	v_exp_f32_e32 v0, v0
	v_exp_f32_e32 v156, v156
	v_exp_f32_e32 v157, v157
	v_exp_f32_e32 v161, v161
	v_add_f32_e32 v160, 1.0, v160
	v_add_f32_e32 v162, 1.0, v162
	v_add_f32_e32 v0, 1.0, v0
	v_add_f32_e32 v156, 1.0, v156
	v_add_f32_e32 v157, 1.0, v157
	v_rcp_f32_e32 v160, v160
	v_add_f32_e32 v161, 1.0, v161
	v_rcp_f32_e32 v162, v162
	v_rcp_f32_e32 v0, v0
	v_rcp_f32_e32 v156, v156
	v_rcp_f32_e32 v157, v157
	v_rcp_f32_e32 v161, v161
	v_cvt_pk_bf16_f32 v158, v158, v159
	v_cvt_pk_bf16_f32 v159, v160, v162
	v_add_co_u32_e32 v160, vcc, s2, v148
	v_cvt_pk_bf16_f32 v156, v0, v156
	v_cvt_pk_bf16_f32 v157, v157, v161
	v_addc_co_u32_e32 v161, vcc, 0, v149, vcc
	global_store_dwordx4 v[160:161], v[156:159], off
	s_waitcnt vmcnt(1)
; DI float sigmoidf_(float x) { return __builtin_amdgcn_rcpf(1.f + fast_exp(-x)); }
; #define PK8(v0, v1) ((u32x4){pk2((v0)[0], (v0)[1]), pk2((v0)[2], (v0)[3]), pk2((v1)[0], (v1)[1]), pk2((v1)[2], (v1)[3])})
;     DI void operator()(const f32x4 (&acc)[2][2][4][2], const Unit& u, int wr, int wc, int fr, int fq, int tid, LAS unsigned char* lds) const {
;     ...
; #pragma unroll
;             for (int ai = 0; ai < 2; ++ai)
; #pragma unroll
;                 for (int m = 0; m < 4; ++m)
; #pragma unroll
;                     for (int bj = 0; bj < 2; ++bj) { f32x4 g0, g1;
;                         const f32x4 a0 = acc[ai][bj][m][0] * rs[ai][m] + bv[bj][0], a1 = acc[ai][bj][m][1] * rs[ai][m] + bv[bj][1];
; #pragma unroll
;                         for (int e = 0; e < 4; ++e) { g0[e] = sigmoidf_(a0[e]); g1[e] = sigmoidf_(a1[e]); }
;                         st[((ai * 4 + m) * 2 + bj) * 512] = PK8(g0, g1); }
	v_fma_f32 v0, v118, v154, v134
	v_fma_f32 v160, v116, v154, v132
	v_fma_f32 v156, v114, v154, v130
	v_fma_f32 v157, v115, v154, v131
	v_mul_f32_e32 v156, 0xbfb8aa3b, v156
	v_mul_f32_e32 v157, 0xbfb8aa3b, v157
	v_exp_f32_e32 v156, v156
	v_exp_f32_e32 v157, v157
	v_fma_f32 v161, v121, v154, v137
	v_mul_f32_e32 v160, 0xbfb8aa3b, v160
	v_add_f32_e32 v156, 1.0, v156
	v_add_f32_e32 v157, 1.0, v157
	v_rcp_f32_e32 v158, v156
	v_fma_f32 v156, v119, v154, v135
	v_rcp_f32_e32 v159, v157
	v_fma_f32 v157, v120, v154, v136
	v_fma_f32 v154, v117, v154, v133
	v_mul_f32_e32 v154, 0xbfb8aa3b, v154
	v_mul_f32_e32 v0, 0xbfb8aa3b, v0
	v_mul_f32_e32 v156, 0xbfb8aa3b, v156
	v_mul_f32_e32 v157, 0xbfb8aa3b, v157
	v_exp_f32_e32 v160, v160
	v_mul_f32_e32 v161, 0xbfb8aa3b, v161
	v_exp_f32_e32 v154, v154
	v_exp_f32_e32 v0, v0
	v_exp_f32_e32 v156, v156
	v_exp_f32_e32 v157, v157
	v_exp_f32_e32 v161, v161
	v_add_f32_e32 v160, 1.0, v160
	v_add_f32_e32 v154, 1.0, v154
	v_add_f32_e32 v0, 1.0, v0
	v_add_f32_e32 v156, 1.0, v156
	v_add_f32_e32 v157, 1.0, v157
	v_rcp_f32_e32 v160, v160
	v_add_f32_e32 v161, 1.0, v161
	v_rcp_f32_e32 v154, v154
	v_rcp_f32_e32 v0, v0
	v_rcp_f32_e32 v156, v156
	v_rcp_f32_e32 v157, v157
	v_rcp_f32_e32 v161, v161
	s_mov_b32 s2, 0x17a02000
	v_cvt_pk_bf16_f32 v158, v158, v159
	v_cvt_pk_bf16_f32 v159, v160, v154
	v_add_co_u32_e32 v160, vcc, s2, v148
	v_cvt_pk_bf16_f32 v156, v0, v156
	v_cvt_pk_bf16_f32 v157, v157, v161
	v_addc_co_u32_e32 v161, vcc, 0, v149, vcc
	global_store_dwordx4 v[160:161], v[156:159], off
	v_fma_f32 v154, v106, v155, v138
	v_mul_f32_e32 v154, 0xbfb8aa3b, v154
	v_fma_f32 v157, v107, v155, v139
	v_mul_f32_e32 v157, 0xbfb8aa3b, v157
	v_exp_f32_e32 v157, v157
	v_exp_f32_e32 v154, v154
	v_fma_f32 v160, v113, v155, v145
	v_fma_f32 v0, v110, v155, v142
	v_add_f32_e32 v157, 1.0, v157
	v_rcp_f32_e32 v158, v157
	v_fma_f32 v157, v112, v155, v144
	v_fma_f32 v156, v111, v155, v143
	v_mul_f32_e32 v157, 0xbfb8aa3b, v157
	v_fma_f32 v159, v108, v155, v140
	v_mul_f32_e32 v160, 0xbfb8aa3b, v160
	v_fma_f32 v161, v109, v155, v141
	v_mul_f32_e32 v0, 0xbfb8aa3b, v0
	v_add_f32_e32 v154, 1.0, v154
	v_mul_f32_e32 v156, 0xbfb8aa3b, v156
	v_exp_f32_e32 v157, v157
	v_mul_f32_e32 v159, 0xbfb8aa3b, v159
	v_exp_f32_e32 v160, v160
	v_mul_f32_e32 v161, 0xbfb8aa3b, v161
	v_exp_f32_e32 v0, v0
	v_rcp_f32_e32 v154, v154
	v_exp_f32_e32 v156, v156
	v_exp_f32_e32 v159, v159
	v_exp_f32_e32 v161, v161
	v_add_f32_e32 v157, 1.0, v157
	v_add_f32_e32 v160, 1.0, v160
	v_add_f32_e32 v0, 1.0, v0
	v_add_f32_e32 v156, 1.0, v156
	v_rcp_f32_e32 v157, v157
	v_add_f32_e32 v159, 1.0, v159
	v_rcp_f32_e32 v160, v160
	v_add_f32_e32 v161, 1.0, v161
	v_cvt_pk_bf16_f32 v158, v154, v158
	v_fma_f32 v154, v98, v155, v130
	v_rcp_f32_e32 v0, v0
	v_rcp_f32_e32 v156, v156
	v_rcp_f32_e32 v159, v159
	v_rcp_f32_e32 v161, v161
	v_mul_f32_e32 v154, 0xbfb8aa3b, v154
	v_exp_f32_e32 v154, v154
	s_mov_b32 s2, 0x17a04000
	v_cvt_pk_bf16_f32 v157, v157, v160
	v_add_co_u32_e32 v160, vcc, s2, v148
	v_cvt_pk_bf16_f32 v156, v0, v156
	v_cvt_pk_bf16_f32 v159, v159, v161
	v_addc_co_u32_e32 v161, vcc, 0, v149, vcc
	global_store_dwordx4 v[160:161], v[156:159], off
	v_add_f32_e32 v154, 1.0, v154
	v_fma_f32 v160, v105, v155, v137
	v_fma_f32 v158, v104, v155, v136
	v_fma_f32 v0, v102, v155, v134
	v_rcp_f32_e32 v156, v154
	v_fma_f32 v154, v103, v155, v135
	v_fma_f32 v157, v99, v155, v131
	v_mul_f32_e32 v158, 0xbfb8aa3b, v158
	v_fma_f32 v159, v100, v155, v132
	v_mul_f32_e32 v160, 0xbfb8aa3b, v160
	v_fma_f32 v155, v101, v155, v133
	v_mul_f32_e32 v0, 0xbfb8aa3b, v0
	v_mul_f32_e32 v154, 0xbfb8aa3b, v154
	v_mul_f32_e32 v157, 0xbfb8aa3b, v157
	v_exp_f32_e32 v158, v158
	v_mul_f32_e32 v159, 0xbfb8aa3b, v159
	v_exp_f32_e32 v160, v160
	v_mul_f32_e32 v155, 0xbfb8aa3b, v155
	v_exp_f32_e32 v0, v0
	v_exp_f32_e32 v154, v154
	v_exp_f32_e32 v157, v157
	v_exp_f32_e32 v159, v159
	v_exp_f32_e32 v155, v155
	v_add_f32_e32 v158, 1.0, v158
	v_add_f32_e32 v160, 1.0, v160
	v_add_f32_e32 v0, 1.0, v0
	v_add_f32_e32 v154, 1.0, v154
	v_add_f32_e32 v157, 1.0, v157
	v_rcp_f32_e32 v158, v158
	v_add_f32_e32 v159, 1.0, v159
	v_rcp_f32_e32 v160, v160
	v_add_f32_e32 v155, 1.0, v155
	v_rcp_f32_e32 v0, v0
	v_rcp_f32_e32 v154, v154
	v_rcp_f32_e32 v157, v157
	v_rcp_f32_e32 v159, v159
	v_rcp_f32_e32 v161, v155
	s_mov_b32 s2, 0x17a06000
	v_cvt_pk_bf16_f32 v155, v158, v160
	v_add_co_u32_e32 v158, vcc, s2, v148
	v_cvt_pk_bf16_f32 v154, v0, v154
	v_cvt_pk_bf16_f32 v156, v156, v157
	v_cvt_pk_bf16_f32 v157, v159, v161
	v_addc_co_u32_e32 v159, vcc, 0, v149, vcc
	global_store_dwordx4 v[158:159], v[154:157], off
	s_waitcnt lgkmcnt(2)
; DI float sigmoidf_(float x) { return __builtin_amdgcn_rcpf(1.f + fast_exp(-x)); }
; #define PK8(v0, v1) ((u32x4){pk2((v0)[0], (v0)[1]), pk2((v0)[2], (v0)[3]), pk2((v1)[0], (v1)[1]), pk2((v1)[2], (v1)[3])})
;     DI void operator()(const f32x4 (&acc)[2][2][4][2], const Unit& u, int wr, int wc, int fr, int fq, int tid, LAS unsigned char* lds) const {
;     ...
; #pragma unroll
;             for (int ai = 0; ai < 2; ++ai)
; #pragma unroll
;                 for (int m = 0; m < 4; ++m)
; #pragma unroll
;                     for (int bj = 0; bj < 2; ++bj) { f32x4 g0, g1;
;                         const f32x4 a0 = acc[ai][bj][m][0] * rs[ai][m] + bv[bj][0], a1 = acc[ai][bj][m][1] * rs[ai][m] + bv[bj][1];
; #pragma unroll
;                         for (int e = 0; e < 4; ++e) { g0[e] = sigmoidf_(a0[e]); g1[e] = sigmoidf_(a1[e]); }
;                         st[((ai * 4 + m) * 2 + bj) * 512] = PK8(g0, g1); }
	v_fma_f32 v158, v92, v152, v140
	v_fma_f32 v160, v93, v152, v141
	v_fma_f32 v154, v90, v152, v138
	v_fma_f32 v155, v91, v152, v139
	v_mul_f32_e32 v154, 0xbfb8aa3b, v154
	v_mul_f32_e32 v155, 0xbfb8aa3b, v155
	v_exp_f32_e32 v154, v154
	v_exp_f32_e32 v155, v155
	v_fma_f32 v0, v94, v152, v142
	v_mul_f32_e32 v158, 0xbfb8aa3b, v158
	v_add_f32_e32 v154, 1.0, v154
	v_add_f32_e32 v155, 1.0, v155
	v_rcp_f32_e32 v156, v154
	v_fma_f32 v154, v95, v152, v143
	v_rcp_f32_e32 v157, v155
	v_fma_f32 v155, v96, v152, v144
	v_fma_f32 v159, v97, v152, v145
	v_mul_f32_e32 v160, 0xbfb8aa3b, v160
	v_mul_f32_e32 v0, 0xbfb8aa3b, v0
	v_mul_f32_e32 v154, 0xbfb8aa3b, v154
	v_mul_f32_e32 v155, 0xbfb8aa3b, v155
	v_exp_f32_e32 v158, v158
	v_mul_f32_e32 v159, 0xbfb8aa3b, v159
	v_exp_f32_e32 v160, v160
	v_exp_f32_e32 v0, v0
	v_exp_f32_e32 v154, v154
	v_exp_f32_e32 v155, v155
	v_exp_f32_e32 v159, v159
	v_add_f32_e32 v158, 1.0, v158
	v_add_f32_e32 v160, 1.0, v160
	v_add_f32_e32 v0, 1.0, v0
	v_add_f32_e32 v154, 1.0, v154
	v_add_f32_e32 v155, 1.0, v155
	v_rcp_f32_e32 v158, v158
	v_add_f32_e32 v159, 1.0, v159
	v_rcp_f32_e32 v160, v160
	v_rcp_f32_e32 v0, v0
	v_rcp_f32_e32 v154, v154
	v_rcp_f32_e32 v155, v155
	v_rcp_f32_e32 v159, v159
	s_mov_b32 s2, 0x17a08000
	v_cvt_pk_bf16_f32 v156, v156, v157
	v_cvt_pk_bf16_f32 v157, v158, v160
	v_add_co_u32_e32 v158, vcc, s2, v148
	v_cvt_pk_bf16_f32 v154, v0, v154
	v_cvt_pk_bf16_f32 v155, v155, v159
	v_addc_co_u32_e32 v159, vcc, 0, v149, vcc
	global_store_dwordx4 v[158:159], v[154:157], off
	v_fma_f32 v0, v86, v152, v134
	v_fma_f32 v158, v84, v152, v132
	v_fma_f32 v154, v82, v152, v130
	v_fma_f32 v155, v83, v152, v131
	v_mul_f32_e32 v154, 0xbfb8aa3b, v154
	v_mul_f32_e32 v155, 0xbfb8aa3b, v155
	v_exp_f32_e32 v154, v154
	v_exp_f32_e32 v155, v155
	v_fma_f32 v159, v89, v152, v137
	v_mul_f32_e32 v158, 0xbfb8aa3b, v158
	v_add_f32_e32 v154, 1.0, v154
	v_add_f32_e32 v155, 1.0, v155
	v_rcp_f32_e32 v156, v154
	v_fma_f32 v154, v87, v152, v135
	v_rcp_f32_e32 v157, v155
	v_fma_f32 v155, v88, v152, v136
	v_fma_f32 v152, v85, v152, v133
	v_mul_f32_e32 v152, 0xbfb8aa3b, v152
	v_mul_f32_e32 v0, 0xbfb8aa3b, v0
	v_mul_f32_e32 v154, 0xbfb8aa3b, v154
	v_mul_f32_e32 v155, 0xbfb8aa3b, v155
	v_exp_f32_e32 v158, v158
	v_mul_f32_e32 v159, 0xbfb8aa3b, v159
	v_exp_f32_e32 v152, v152
	v_exp_f32_e32 v0, v0
	v_exp_f32_e32 v154, v154
	v_exp_f32_e32 v155, v155
	v_exp_f32_e32 v159, v159
	v_add_f32_e32 v158, 1.0, v158
	v_add_f32_e32 v152, 1.0, v152
	v_add_f32_e32 v0, 1.0, v0
	v_add_f32_e32 v154, 1.0, v154
	v_add_f32_e32 v155, 1.0, v155
	v_rcp_f32_e32 v158, v158
	v_add_f32_e32 v159, 1.0, v159
	v_rcp_f32_e32 v152, v152
	v_rcp_f32_e32 v0, v0
	v_rcp_f32_e32 v154, v154
	v_rcp_f32_e32 v155, v155
	v_rcp_f32_e32 v159, v159
	s_mov_b32 s2, 0x17a0a000
	v_cvt_pk_bf16_f32 v156, v156, v157
	v_cvt_pk_bf16_f32 v157, v158, v152
	v_add_co_u32_e32 v158, vcc, s2, v148
	v_cvt_pk_bf16_f32 v154, v0, v154
	v_cvt_pk_bf16_f32 v155, v155, v159
	v_addc_co_u32_e32 v159, vcc, 0, v149, vcc
	global_store_dwordx4 v[158:159], v[154:157], off
	v_fma_f32 v152, v74, v153, v138
	v_mul_f32_e32 v152, 0xbfb8aa3b, v152
	v_fma_f32 v155, v75, v153, v139
	v_mul_f32_e32 v155, 0xbfb8aa3b, v155
	v_exp_f32_e32 v155, v155
	v_exp_f32_e32 v152, v152
	v_fma_f32 v158, v81, v153, v145
	v_fma_f32 v0, v78, v153, v142
	v_add_f32_e32 v155, 1.0, v155
	v_rcp_f32_e32 v156, v155
	v_fma_f32 v155, v80, v153, v144
	v_fma_f32 v154, v79, v153, v143
	v_mul_f32_e32 v155, 0xbfb8aa3b, v155
	v_fma_f32 v157, v76, v153, v140
	v_mul_f32_e32 v158, 0xbfb8aa3b, v158
	v_fma_f32 v159, v77, v153, v141
	v_mul_f32_e32 v0, 0xbfb8aa3b, v0
	v_add_f32_e32 v152, 1.0, v152
	v_mul_f32_e32 v154, 0xbfb8aa3b, v154
	v_exp_f32_e32 v155, v155
	v_mul_f32_e32 v157, 0xbfb8aa3b, v157
	v_exp_f32_e32 v158, v158
	v_mul_f32_e32 v159, 0xbfb8aa3b, v159
	v_exp_f32_e32 v0, v0
	v_rcp_f32_e32 v152, v152
	v_exp_f32_e32 v154, v154
	v_exp_f32_e32 v157, v157
	v_exp_f32_e32 v159, v159
	v_add_f32_e32 v155, 1.0, v155
	v_add_f32_e32 v158, 1.0, v158
	v_add_f32_e32 v0, 1.0, v0
	v_add_f32_e32 v154, 1.0, v154
	v_rcp_f32_e32 v155, v155
	v_add_f32_e32 v157, 1.0, v157
	v_rcp_f32_e32 v158, v158
	v_add_f32_e32 v159, 1.0, v159
	v_cvt_pk_bf16_f32 v156, v152, v156
	v_fma_f32 v152, v66, v153, v130
	v_rcp_f32_e32 v0, v0
	v_rcp_f32_e32 v154, v154
	v_rcp_f32_e32 v157, v157
	v_rcp_f32_e32 v159, v159
	v_mul_f32_e32 v152, 0xbfb8aa3b, v152
	v_exp_f32_e32 v152, v152
	s_mov_b32 s2, 0x17a0c000
	v_cvt_pk_bf16_f32 v155, v155, v158
	v_add_co_u32_e32 v158, vcc, s2, v148
	v_cvt_pk_bf16_f32 v154, v0, v154
	v_cvt_pk_bf16_f32 v157, v157, v159
	v_addc_co_u32_e32 v159, vcc, 0, v149, vcc
	global_store_dwordx4 v[158:159], v[154:157], off
	v_add_f32_e32 v152, 1.0, v152
	v_fma_f32 v158, v73, v153, v137
	v_fma_f32 v156, v72, v153, v136
	v_fma_f32 v0, v70, v153, v134
	v_rcp_f32_e32 v154, v152
	v_fma_f32 v152, v71, v153, v135
	v_fma_f32 v155, v67, v153, v131
	v_mul_f32_e32 v156, 0xbfb8aa3b, v156
	v_fma_f32 v157, v68, v153, v132
	v_mul_f32_e32 v158, 0xbfb8aa3b, v158
	v_fma_f32 v153, v69, v153, v133
	v_mul_f32_e32 v0, 0xbfb8aa3b, v0
	v_mul_f32_e32 v152, 0xbfb8aa3b, v152
	v_mul_f32_e32 v155, 0xbfb8aa3b, v155
	v_exp_f32_e32 v156, v156
	v_mul_f32_e32 v157, 0xbfb8aa3b, v157
	v_exp_f32_e32 v158, v158
	v_mul_f32_e32 v153, 0xbfb8aa3b, v153
	v_exp_f32_e32 v0, v0
	v_exp_f32_e32 v152, v152
	v_exp_f32_e32 v155, v155
	v_exp_f32_e32 v157, v157
	v_exp_f32_e32 v153, v153
	v_add_f32_e32 v156, 1.0, v156
	v_add_f32_e32 v158, 1.0, v158
	v_add_f32_e32 v0, 1.0, v0
	v_add_f32_e32 v152, 1.0, v152
	v_add_f32_e32 v155, 1.0, v155
	v_rcp_f32_e32 v156, v156
	v_add_f32_e32 v157, 1.0, v157
	v_rcp_f32_e32 v158, v158
	v_add_f32_e32 v153, 1.0, v153
	v_rcp_f32_e32 v0, v0
	v_rcp_f32_e32 v152, v152
	v_rcp_f32_e32 v155, v155
	v_rcp_f32_e32 v157, v157
	v_rcp_f32_e32 v159, v153
	s_mov_b32 s2, 0x17a0e000
	v_cvt_pk_bf16_f32 v153, v156, v158
	v_add_co_u32_e32 v156, vcc, s2, v148
	v_cvt_pk_bf16_f32 v152, v0, v152
	v_cvt_pk_bf16_f32 v154, v154, v155
	v_cvt_pk_bf16_f32 v155, v157, v159
	v_addc_co_u32_e32 v157, vcc, 0, v149, vcc
	global_store_dwordx4 v[156:157], v[152:155], off
	s_waitcnt lgkmcnt(1)
; DI float sigmoidf_(float x) { return __builtin_amdgcn_rcpf(1.f + fast_exp(-x)); }
; #define PK8(v0, v1) ((u32x4){pk2((v0)[0], (v0)[1]), pk2((v0)[2], (v0)[3]), pk2((v1)[0], (v1)[1]), pk2((v1)[2], (v1)[3])})
;     DI void operator()(const f32x4 (&acc)[2][2][4][2], const Unit& u, int wr, int wc, int fr, int fq, int tid, LAS unsigned char* lds) const {
;     ...
; #pragma unroll
;             for (int ai = 0; ai < 2; ++ai)
; #pragma unroll
;                 for (int m = 0; m < 4; ++m)
; #pragma unroll
;                     for (int bj = 0; bj < 2; ++bj) { f32x4 g0, g1;
;                         const f32x4 a0 = acc[ai][bj][m][0] * rs[ai][m] + bv[bj][0], a1 = acc[ai][bj][m][1] * rs[ai][m] + bv[bj][1];
; #pragma unroll
;                         for (int e = 0; e < 4; ++e) { g0[e] = sigmoidf_(a0[e]); g1[e] = sigmoidf_(a1[e]); }
;                         st[((ai * 4 + m) * 2 + bj) * 512] = PK8(g0, g1); }
	v_fma_f32 v156, v60, v150, v140
	v_fma_f32 v158, v61, v150, v141
	v_fma_f32 v152, v58, v150, v138
	v_fma_f32 v153, v59, v150, v139
	v_mul_f32_e32 v152, 0xbfb8aa3b, v152
	v_mul_f32_e32 v153, 0xbfb8aa3b, v153
	v_exp_f32_e32 v152, v152
	v_exp_f32_e32 v153, v153
	v_fma_f32 v0, v62, v150, v142
	v_mul_f32_e32 v156, 0xbfb8aa3b, v156
	v_add_f32_e32 v152, 1.0, v152
	v_add_f32_e32 v153, 1.0, v153
	v_rcp_f32_e32 v154, v152
	v_fma_f32 v152, v63, v150, v143
	v_rcp_f32_e32 v155, v153
	v_fma_f32 v153, v64, v150, v144
	v_fma_f32 v157, v65, v150, v145
	v_mul_f32_e32 v158, 0xbfb8aa3b, v158
	v_mul_f32_e32 v0, 0xbfb8aa3b, v0
	v_mul_f32_e32 v152, 0xbfb8aa3b, v152
	v_mul_f32_e32 v153, 0xbfb8aa3b, v153
	v_exp_f32_e32 v156, v156
	v_mul_f32_e32 v157, 0xbfb8aa3b, v157
	v_exp_f32_e32 v158, v158
	v_exp_f32_e32 v0, v0
	v_exp_f32_e32 v152, v152
	v_exp_f32_e32 v153, v153
	v_exp_f32_e32 v157, v157
	v_add_f32_e32 v156, 1.0, v156
	v_add_f32_e32 v158, 1.0, v158
	v_add_f32_e32 v0, 1.0, v0
	v_add_f32_e32 v152, 1.0, v152
	v_add_f32_e32 v153, 1.0, v153
	v_rcp_f32_e32 v156, v156
	v_add_f32_e32 v157, 1.0, v157
	v_rcp_f32_e32 v158, v158
	v_rcp_f32_e32 v0, v0
	v_rcp_f32_e32 v152, v152
	v_rcp_f32_e32 v153, v153
	v_rcp_f32_e32 v157, v157
	s_mov_b32 s2, 0x17a10000
	v_cvt_pk_bf16_f32 v154, v154, v155
	v_cvt_pk_bf16_f32 v155, v156, v158
	v_add_co_u32_e32 v156, vcc, s2, v148
	v_cvt_pk_bf16_f32 v152, v0, v152
	v_cvt_pk_bf16_f32 v153, v153, v157
	v_addc_co_u32_e32 v157, vcc, 0, v149, vcc
	global_store_dwordx4 v[156:157], v[152:155], off
	v_fma_f32 v0, v54, v150, v134
	v_fma_f32 v156, v52, v150, v132
	v_fma_f32 v152, v50, v150, v130
	v_fma_f32 v153, v51, v150, v131
	v_mul_f32_e32 v152, 0xbfb8aa3b, v152
	v_mul_f32_e32 v153, 0xbfb8aa3b, v153
	v_exp_f32_e32 v152, v152
	v_exp_f32_e32 v153, v153
	v_fma_f32 v157, v57, v150, v137
	v_mul_f32_e32 v156, 0xbfb8aa3b, v156
	v_add_f32_e32 v152, 1.0, v152
	v_add_f32_e32 v153, 1.0, v153
	v_rcp_f32_e32 v154, v152
	v_fma_f32 v152, v55, v150, v135
	v_rcp_f32_e32 v155, v153
	v_fma_f32 v153, v56, v150, v136
	v_fma_f32 v150, v53, v150, v133
	v_mul_f32_e32 v150, 0xbfb8aa3b, v150
	v_mul_f32_e32 v0, 0xbfb8aa3b, v0
	v_mul_f32_e32 v152, 0xbfb8aa3b, v152
	v_mul_f32_e32 v153, 0xbfb8aa3b, v153
	v_exp_f32_e32 v156, v156
	v_mul_f32_e32 v157, 0xbfb8aa3b, v157
	v_exp_f32_e32 v150, v150
	v_exp_f32_e32 v0, v0
	v_exp_f32_e32 v152, v152
	v_exp_f32_e32 v153, v153
	v_exp_f32_e32 v157, v157
	v_add_f32_e32 v156, 1.0, v156
	v_add_f32_e32 v150, 1.0, v150
	v_add_f32_e32 v0, 1.0, v0
	v_add_f32_e32 v152, 1.0, v152
	v_add_f32_e32 v153, 1.0, v153
	v_rcp_f32_e32 v156, v156
	v_add_f32_e32 v157, 1.0, v157
	v_rcp_f32_e32 v150, v150
	v_rcp_f32_e32 v0, v0
	v_rcp_f32_e32 v152, v152
	v_rcp_f32_e32 v153, v153
	v_rcp_f32_e32 v157, v157
	s_mov_b32 s2, 0x17a12000
	v_cvt_pk_bf16_f32 v154, v154, v155
	v_cvt_pk_bf16_f32 v155, v156, v150
	v_add_co_u32_e32 v156, vcc, s2, v148
	v_cvt_pk_bf16_f32 v152, v0, v152
	v_cvt_pk_bf16_f32 v153, v153, v157
	v_addc_co_u32_e32 v157, vcc, 0, v149, vcc
	global_store_dwordx4 v[156:157], v[152:155], off
	v_fma_f32 v150, v42, v151, v138
	v_mul_f32_e32 v150, 0xbfb8aa3b, v150
	v_fma_f32 v153, v43, v151, v139
	v_mul_f32_e32 v153, 0xbfb8aa3b, v153
	v_exp_f32_e32 v153, v153
	v_exp_f32_e32 v150, v150
	v_fma_f32 v156, v49, v151, v145
	v_fma_f32 v0, v46, v151, v142
	v_add_f32_e32 v153, 1.0, v153
	v_rcp_f32_e32 v154, v153
	v_fma_f32 v153, v48, v151, v144
	v_fma_f32 v152, v47, v151, v143
	v_mul_f32_e32 v153, 0xbfb8aa3b, v153
	v_fma_f32 v155, v44, v151, v140
	v_mul_f32_e32 v156, 0xbfb8aa3b, v156
	v_fma_f32 v157, v45, v151, v141
	v_mul_f32_e32 v0, 0xbfb8aa3b, v0
	v_add_f32_e32 v150, 1.0, v150
	v_mul_f32_e32 v152, 0xbfb8aa3b, v152
	v_exp_f32_e32 v153, v153
	v_mul_f32_e32 v155, 0xbfb8aa3b, v155
	v_exp_f32_e32 v156, v156
	v_mul_f32_e32 v157, 0xbfb8aa3b, v157
	v_exp_f32_e32 v0, v0
	v_rcp_f32_e32 v150, v150
	v_exp_f32_e32 v152, v152
	v_exp_f32_e32 v155, v155
	v_exp_f32_e32 v157, v157
	v_add_f32_e32 v153, 1.0, v153
	v_add_f32_e32 v156, 1.0, v156
	v_add_f32_e32 v0, 1.0, v0
	v_add_f32_e32 v152, 1.0, v152
	v_rcp_f32_e32 v153, v153
	v_add_f32_e32 v155, 1.0, v155
	v_rcp_f32_e32 v156, v156
	v_add_f32_e32 v157, 1.0, v157
	v_cvt_pk_bf16_f32 v154, v150, v154
	v_fma_f32 v150, v34, v151, v130
	v_rcp_f32_e32 v0, v0
	v_rcp_f32_e32 v152, v152
	v_rcp_f32_e32 v155, v155
	v_rcp_f32_e32 v157, v157
	v_mul_f32_e32 v150, 0xbfb8aa3b, v150
	v_exp_f32_e32 v150, v150
	s_mov_b32 s2, 0x17a14000
	v_cvt_pk_bf16_f32 v153, v153, v156
	v_add_co_u32_e32 v156, vcc, s2, v148
	v_cvt_pk_bf16_f32 v152, v0, v152
	v_cvt_pk_bf16_f32 v155, v155, v157
	v_addc_co_u32_e32 v157, vcc, 0, v149, vcc
	global_store_dwordx4 v[156:157], v[152:155], off
	v_add_f32_e32 v150, 1.0, v150
	v_fma_f32 v156, v41, v151, v137
	v_fma_f32 v154, v40, v151, v136
	v_fma_f32 v0, v38, v151, v134
	v_rcp_f32_e32 v152, v150
	v_fma_f32 v150, v39, v151, v135
	v_fma_f32 v153, v35, v151, v131
	v_mul_f32_e32 v154, 0xbfb8aa3b, v154
	v_fma_f32 v155, v36, v151, v132
	v_mul_f32_e32 v156, 0xbfb8aa3b, v156
	v_fma_f32 v151, v37, v151, v133
	v_mul_f32_e32 v0, 0xbfb8aa3b, v0
	v_mul_f32_e32 v150, 0xbfb8aa3b, v150
	v_mul_f32_e32 v153, 0xbfb8aa3b, v153
	v_exp_f32_e32 v154, v154
	v_mul_f32_e32 v155, 0xbfb8aa3b, v155
	v_exp_f32_e32 v156, v156
	v_mul_f32_e32 v151, 0xbfb8aa3b, v151
	v_exp_f32_e32 v0, v0
	v_exp_f32_e32 v150, v150
	v_exp_f32_e32 v153, v153
	v_exp_f32_e32 v155, v155
	v_exp_f32_e32 v151, v151
	v_add_f32_e32 v154, 1.0, v154
	v_add_f32_e32 v156, 1.0, v156
	v_add_f32_e32 v0, 1.0, v0
	v_add_f32_e32 v150, 1.0, v150
	v_add_f32_e32 v153, 1.0, v153
	v_rcp_f32_e32 v154, v154
	v_add_f32_e32 v155, 1.0, v155
	v_rcp_f32_e32 v156, v156
	v_add_f32_e32 v151, 1.0, v151
	v_rcp_f32_e32 v0, v0
	v_rcp_f32_e32 v150, v150
	v_rcp_f32_e32 v153, v153
	v_rcp_f32_e32 v155, v155
	v_rcp_f32_e32 v157, v151
	s_mov_b32 s2, 0x17a16000
	v_cvt_pk_bf16_f32 v151, v154, v156
	v_add_co_u32_e32 v154, vcc, s2, v148
	v_cvt_pk_bf16_f32 v150, v0, v150
	v_cvt_pk_bf16_f32 v152, v152, v153
	v_cvt_pk_bf16_f32 v153, v155, v157
	v_addc_co_u32_e32 v155, vcc, 0, v149, vcc
	global_store_dwordx4 v[154:155], v[150:153], off
	s_waitcnt lgkmcnt(0)
; DI float sigmoidf_(float x) { return __builtin_amdgcn_rcpf(1.f + fast_exp(-x)); }
; #define PK8(v0, v1) ((u32x4){pk2((v0)[0], (v0)[1]), pk2((v0)[2], (v0)[3]), pk2((v1)[0], (v1)[1]), pk2((v1)[2], (v1)[3])})
;     DI void operator()(const f32x4 (&acc)[2][2][4][2], const Unit& u, int wr, int wc, int fr, int fq, int tid, LAS unsigned char* lds) const {
;     ...
; #pragma unroll
;             for (int ai = 0; ai < 2; ++ai)
; #pragma unroll
;                 for (int m = 0; m < 4; ++m)
; #pragma unroll
;                     for (int bj = 0; bj < 2; ++bj) { f32x4 g0, g1;
;                         const f32x4 a0 = acc[ai][bj][m][0] * rs[ai][m] + bv[bj][0], a1 = acc[ai][bj][m][1] * rs[ai][m] + bv[bj][1];
; #pragma unroll
;                         for (int e = 0; e < 4; ++e) { g0[e] = sigmoidf_(a0[e]); g1[e] = sigmoidf_(a1[e]); }
;                         st[((ai * 4 + m) * 2 + bj) * 512] = PK8(g0, g1); }
	v_fma_f32 v154, v28, v146, v140
	v_fma_f32 v156, v29, v146, v141
	v_fma_f32 v150, v26, v146, v138
	v_fma_f32 v151, v27, v146, v139
	v_mul_f32_e32 v150, 0xbfb8aa3b, v150
	v_mul_f32_e32 v151, 0xbfb8aa3b, v151
	v_exp_f32_e32 v150, v150
	v_exp_f32_e32 v151, v151
	v_fma_f32 v0, v30, v146, v142
	v_mul_f32_e32 v154, 0xbfb8aa3b, v154
	v_add_f32_e32 v150, 1.0, v150
	v_add_f32_e32 v151, 1.0, v151
	v_rcp_f32_e32 v152, v150
	v_fma_f32 v150, v31, v146, v143
	v_rcp_f32_e32 v153, v151
	v_fma_f32 v151, v32, v146, v144
	v_fma_f32 v155, v33, v146, v145
	v_mul_f32_e32 v156, 0xbfb8aa3b, v156
	v_mul_f32_e32 v0, 0xbfb8aa3b, v0
	v_mul_f32_e32 v150, 0xbfb8aa3b, v150
	v_mul_f32_e32 v151, 0xbfb8aa3b, v151
	v_exp_f32_e32 v154, v154
	v_mul_f32_e32 v155, 0xbfb8aa3b, v155
	v_exp_f32_e32 v156, v156
	v_exp_f32_e32 v0, v0
	v_exp_f32_e32 v150, v150
	v_exp_f32_e32 v151, v151
	v_exp_f32_e32 v155, v155
	v_add_f32_e32 v154, 1.0, v154
	v_add_f32_e32 v156, 1.0, v156
	v_add_f32_e32 v0, 1.0, v0
	v_add_f32_e32 v150, 1.0, v150
	v_add_f32_e32 v151, 1.0, v151
	v_rcp_f32_e32 v154, v154
	v_add_f32_e32 v155, 1.0, v155
	v_rcp_f32_e32 v156, v156
	v_rcp_f32_e32 v0, v0
	v_rcp_f32_e32 v150, v150
	v_rcp_f32_e32 v151, v151
	v_rcp_f32_e32 v155, v155
	s_mov_b32 s2, 0x17a18000
	v_cvt_pk_bf16_f32 v152, v152, v153
	v_cvt_pk_bf16_f32 v153, v154, v156
	v_add_co_u32_e32 v154, vcc, s2, v148
	v_cvt_pk_bf16_f32 v150, v0, v150
	v_cvt_pk_bf16_f32 v151, v151, v155
	v_addc_co_u32_e32 v155, vcc, 0, v149, vcc
	global_store_dwordx4 v[154:155], v[150:153], off
	v_fma_f32 v0, v22, v146, v134
	v_mul_f32_e32 v0, 0xbfb8aa3b, v0
	v_fma_f32 v150, v18, v146, v130
	v_mul_f32_e32 v150, 0xbfb8aa3b, v150
	v_exp_f32_e32 v150, v150
	v_exp_f32_e32 v0, v0
	v_fma_f32 v138, v10, v147, v138
	v_mul_f32_e32 v138, 0xbfb8aa3b, v138
	v_add_f32_e32 v150, 1.0, v150
	v_rcp_f32_e32 v152, v150
	v_fma_f32 v150, v23, v146, v135
	v_mul_f32_e32 v150, 0xbfb8aa3b, v150
	v_exp_f32_e32 v150, v150
	v_add_f32_e32 v0, 1.0, v0
	v_exp_f32_e32 v138, v138
	v_rcp_f32_e32 v0, v0
	v_add_f32_e32 v150, 1.0, v150
	v_rcp_f32_e32 v150, v150
	v_add_f32_e32 v138, 1.0, v138
	v_fma_f32 v151, v19, v146, v131
	v_mul_f32_e32 v151, 0xbfb8aa3b, v151
	v_cvt_pk_bf16_f32 v150, v0, v150
	v_fma_f32 v0, v14, v147, v142
	v_rcp_f32_e32 v142, v138
	v_fma_f32 v138, v15, v147, v143
	v_mul_f32_e32 v0, 0xbfb8aa3b, v0
	v_mul_f32_e32 v138, 0xbfb8aa3b, v138
	v_exp_f32_e32 v151, v151
	v_exp_f32_e32 v0, v0
	v_exp_f32_e32 v138, v138
	v_fma_f32 v139, v11, v147, v139
	v_mul_f32_e32 v139, 0xbfb8aa3b, v139
	v_fma_f32 v140, v12, v147, v140
	v_exp_f32_e32 v139, v139
	v_mul_f32_e32 v140, 0xbfb8aa3b, v140
	v_fma_f32 v130, v2, v147, v130
	v_fma_f32 v131, v3, v147, v131
	v_fma_f32 v154, v20, v146, v132
	v_exp_f32_e32 v140, v140
	v_mul_f32_e32 v130, 0xbfb8aa3b, v130
	v_mul_f32_e32 v131, 0xbfb8aa3b, v131
	v_fma_f32 v132, v4, v147, v132
	v_add_f32_e32 v151, 1.0, v151
	v_add_f32_e32 v0, 1.0, v0
	v_add_f32_e32 v138, 1.0, v138
	v_exp_f32_e32 v130, v130
	v_exp_f32_e32 v131, v131
	v_mul_f32_e32 v132, 0xbfb8aa3b, v132
	v_rcp_f32_e32 v153, v151
	v_fma_f32 v151, v24, v146, v136
	v_fma_f32 v155, v25, v146, v137
	v_fma_f32 v146, v21, v146, v133
	v_rcp_f32_e32 v0, v0
	v_rcp_f32_e32 v138, v138
	v_exp_f32_e32 v132, v132
	v_mul_f32_e32 v154, 0xbfb8aa3b, v154
	v_mul_f32_e32 v146, 0xbfb8aa3b, v146
	v_add_f32_e32 v139, 1.0, v139
	v_mul_f32_e32 v151, 0xbfb8aa3b, v151
	v_exp_f32_e32 v154, v154
	v_mul_f32_e32 v155, 0xbfb8aa3b, v155
	v_exp_f32_e32 v146, v146
	v_rcp_f32_e32 v143, v139
	v_fma_f32 v139, v16, v147, v144
	v_add_f32_e32 v140, 1.0, v140
	v_fmac_f32_e32 v145, v17, v147
	v_exp_f32_e32 v151, v151
	v_exp_f32_e32 v155, v155
	v_mul_f32_e32 v139, 0xbfb8aa3b, v139
	v_rcp_f32_e32 v144, v140
	v_mul_f32_e32 v140, 0xbfb8aa3b, v145
	v_add_f32_e32 v130, 1.0, v130
	v_add_f32_e32 v131, 1.0, v131
	v_exp_f32_e32 v139, v139
	v_exp_f32_e32 v140, v140
	v_cvt_pk_bf16_f32 v138, v0, v138
	v_fma_f32 v0, v6, v147, v134
	v_rcp_f32_e32 v134, v130
	v_fma_f32 v130, v7, v147, v135
	v_rcp_f32_e32 v135, v131
	v_fma_f32 v131, v8, v147, v136
	v_add_f32_e32 v132, 1.0, v132
	v_fmac_f32_e32 v137, v9, v147
	v_fmac_f32_e32 v141, v13, v147
	v_mul_f32_e32 v131, 0xbfb8aa3b, v131
	v_rcp_f32_e32 v136, v132
	v_mul_f32_e32 v132, 0xbfb8aa3b, v137
	v_fmac_f32_e32 v133, v5, v147
	v_add_f32_e32 v154, 1.0, v154
	v_add_f32_e32 v146, 1.0, v146
	v_mul_f32_e32 v141, 0xbfb8aa3b, v141
	v_mul_f32_e32 v0, 0xbfb8aa3b, v0
	v_mul_f32_e32 v130, 0xbfb8aa3b, v130
	v_exp_f32_e32 v131, v131
	v_exp_f32_e32 v132, v132
	v_mul_f32_e32 v133, 0xbfb8aa3b, v133
	v_add_f32_e32 v151, 1.0, v151
	v_rcp_f32_e32 v154, v154
	v_add_f32_e32 v155, 1.0, v155
	v_rcp_f32_e32 v146, v146
	v_exp_f32_e32 v141, v141
	v_exp_f32_e32 v0, v0
	v_exp_f32_e32 v130, v130
	v_exp_f32_e32 v133, v133
	v_rcp_f32_e32 v151, v151
	v_rcp_f32_e32 v155, v155
	v_add_f32_e32 v139, 1.0, v139
	v_add_f32_e32 v140, 1.0, v140
	v_rcp_f32_e32 v139, v139
	v_rcp_f32_e32 v140, v140
	s_mov_b32 s2, 0x17a1a000
	v_add_f32_e32 v131, 1.0, v131
	v_add_f32_e32 v132, 1.0, v132
	v_cvt_pk_bf16_f32 v152, v152, v153
	v_cvt_pk_bf16_f32 v153, v154, v146
	v_add_co_u32_e32 v154, vcc, s2, v148
	v_add_f32_e32 v141, 1.0, v141
	v_add_f32_e32 v0, 1.0, v0
	v_add_f32_e32 v130, 1.0, v130
	v_rcp_f32_e32 v131, v131
	v_rcp_f32_e32 v132, v132
	v_add_f32_e32 v133, 1.0, v133
	v_cvt_pk_bf16_f32 v151, v151, v155
	v_addc_co_u32_e32 v155, vcc, 0, v149, vcc
	v_rcp_f32_e32 v141, v141
	s_mov_b32 s2, 0x17a1c000
	v_rcp_f32_e32 v0, v0
	v_rcp_f32_e32 v130, v130
	v_rcp_f32_e32 v133, v133
	v_cvt_pk_bf16_f32 v139, v139, v140
	v_cvt_pk_bf16_f32 v140, v142, v143
	v_add_co_u32_e32 v142, vcc, s2, v148
	v_cvt_pk_bf16_f32 v131, v131, v132
	s_nop 0
	v_addc_co_u32_e32 v143, vcc, 0, v149, vcc
	v_cvt_pk_bf16_f32 v132, v134, v135
	v_add_co_u32_e32 v134, vcc, 0x17a1e000, v148
	v_cvt_pk_bf16_f32 v141, v144, v141
	v_cvt_pk_bf16_f32 v130, v0, v130
	v_cvt_pk_bf16_f32 v133, v136, v133
	v_addc_co_u32_e32 v135, vcc, 0, v149, vcc
	global_store_dwordx4 v[154:155], v[150:153], off
	global_store_dwordx4 v[142:143], v[138:141], off
	global_store_dwordx4 v[134:135], v[130:133], off

; #define LAS __attribute__((address_space(3)))
; DI float sum16(const float* p) { const f32x4 a = *(const f32x4*)p, b = *(const f32x4*)(p + 4), c = *(const f32x4*)(p + 8), d = *(const f32x4*)(p + 12); return (((a[0] + a[1]) + (a[2] + a[3])) + ((b[0] + b[1]) + (b[2] + b[3]))) + (((c[0] + c[1]) + (c[2] + c[3])) + ((d[0] + d[1]) + (d[2] + d[3]))); }
; DI float sum4(const float* p) { const f32x4 a = *(const f32x4*)p; return (a[0] + a[1]) + (a[2] + a[3]); }
;     template <int NS> DI void rowstat(float (&rs)[2][4], const float* parts, float inv_n, float mul, int rowbase_wave, LAS float* buf, int lane, int fr) const {
; #pragma unroll
;         for (int h = 0; h < 2; ++h) { const float* pp = parts + (size_t)(rowbase_wave + h * 128 + lane) * (NS == 4 ? 4 : 16);
;             const float sm = NS == 16 ? sum16(pp) : (NS == 12 ? sum12(pp) : sum4(pp)); buf[h * 64 + lane] = __builtin_amdgcn_rsqf(sm * inv_n + EPS) * mul; }
; #pragma unroll
;         for (int ai = 0; ai < 2; ++ai)
; #pragma unroll
;             for (int m = 0; m < 4; ++m) rs[ai][m] = buf[ai * 64 + m * 16 + fr];
;     }
;     DI void operator()(const f32x4 (&acc)[2][2][4][2], const Unit& u, int wr, int wc, int fr, int fq, int tid, LAS unsigned char* lds) const {
;     ...
;         case K_SB: case K_MB: { EPI_CASE_BEGIN
;             const bool ismb = u.kind == K_MB;
;             const int t = u.pn - (ismb ? 11 : 5); bf16_t* dst = (bf16_t*)(ws + (ismb ? WS_MB : WS_SB)); const float sc = t < 2 ? C_MB : 1.f;   const float* rt = (const float*)(ws + WS_ROPEB);
;             const bool rope = ismb && (t < 4) && ((wc & 1) == 0);
;             rowstat<16>(rs, ssq1, 1.f / 1024.f, 1.f, rbw, rsbuf, lane, fr);
;             f32x4 bv[2][2];
; #pragma unroll
;             for (int bj = 0; bj < 2; ++bj)
; #pragma unroll
;                 for (int n = 0; n < 2; ++n) bv[bj][n] = *(const f32x4*)(bias1 + bidx * NWIN + u.pn * 256 + lc0 + bj * 128 + n * 4);
; #pragma unroll
;             for (int ai = 0; ai < 2; ++ai)
; #pragma unroll
;                 for (int m = 0; m < 4; ++m) { const int row = row0 + ai * 128 + m * 16;
;                     f32x4 cs0 = {1.f, 1.f, 1.f, 1.f}, cs1 = cs0, sn0 = {0.f, 0.f, 0.f, 0.f}, sn1 = sn0;
;                     if (rope) { const float* rr = rt + (size_t)row * 16; cs0 = *(const f32x4*)rr; cs1 = *(const f32x4*)(rr + 4); sn0 = *(const f32x4*)(rr + 8); sn1 = *(const f32x4*)(rr + 12); }
.LBB0_607:
	s_andn2_b64 vcc, exec, s[42:43]
	s_cbranch_vccnz .LBB0_793
	s_waitcnt lgkmcnt(0)
	v_mov_b32_e32 v0, v229
	v_mov_b32_e32 v146, v230
	v_mov_b32_e32 v130, v231
	v_readlane_b32 s2, v252, 1
	v_and_b32_e32 v131, 63, v130
	v_lshlrev_b32_e32 v130, 3, v130
	v_and_b32_e32 v130, 0xfffffe00, v130
	v_or_b32_e32 v148, s54, v131
	v_add_u32_e32 v147, s2, v130
	v_ashrrev_i32_e32 v149, 31, v148
	v_lshl_add_u32 v150, v131, 2, v147
	v_lshlrev_b64 v[130:131], 6, v[148:149]
	s_waitcnt vmcnt(0)
	v_lshl_add_u64 v[142:143], s[18:19], 0, v[130:131]
	global_load_dwordx4 v[130:133], v[142:143], off offset:48
	global_load_dwordx4 v[134:137], v[142:143], off offset:32
	global_load_dwordx4 v[138:141], v[142:143], off offset:16
	s_nop 0
	global_load_dwordx4 v[142:145], v[142:143], off
	v_add_u32_e32 v236, 0x80, v148
	v_ashrrev_i32_e32 v237, 31, v236
	v_lshlrev_b64 v[236:237], 6, v[236:237]
	v_lshl_add_u64 v[248:249], s[18:19], 0, v[236:237]
	global_load_dwordx4 v[236:239], v[248:249], off offset:48
	global_load_dwordx4 v[240:243], v[248:249], off offset:32
	global_load_dwordx4 v[244:247], v[248:249], off offset:16
	s_nop 0
	global_load_dwordx4 v[248:251], v[248:249], off
	s_cmp_eq_u32 s55, 4
	s_cselect_b64 s[46:47], -1, 0
	s_and_b64 s[42:43], s[46:47], exec
	s_cselect_b32 s2, -11, -5
	s_add_i32 s2, s2, s38
	s_cmp_lt_i32 s2, 4
	s_mul_i32 s44, s14, 0x1d00
	s_cselect_b64 s[42:43], -1, 0
	s_ashr_i32 s45, s44, 31
	s_lshl_b64 s[44:45], s[44:45], 2
	s_add_u32 s48, s57, s44
	s_addc_u32 s49, s86, s45
	s_lshl_b32 s44, s38, 8
	s_ashr_i32 s45, s44, 31
	s_lshl_b64 s[44:45], s[44:45], 2
	v_lshl_add_u32 v178, v0, 3, s24
	s_add_u32 s44, s48, s44
	s_addc_u32 s45, s49, s45
	v_ashrrev_i32_e32 v179, 31, v178
	v_readlane_b32 s48, v252, 44
	v_readlane_b32 s49, v252, 45
	v_add_u32_e32 v182, s54, v146
	v_ashrrev_i32_e32 v183, 31, v182
	s_waitcnt vmcnt(7)
	v_add_f32_e32 v130, v130, v131
	s_waitcnt vmcnt(6)
	v_add_f32_e32 v134, v134, v135
	s_waitcnt vmcnt(5)
	v_add_f32_e32 v138, v138, v139
	s_waitcnt vmcnt(4)
	v_add_f32_e32 v142, v142, v143
	v_add_f32_e32 v143, v144, v145
	v_add_f32_e32 v139, v140, v141
	v_add_f32_e32 v135, v136, v137
	v_add_f32_e32 v131, v132, v133
	v_add_f32_e32 v142, v142, v143
	v_add_f32_e32 v138, v138, v139
	v_add_f32_e32 v134, v134, v135
	v_add_f32_e32 v130, v130, v131
	v_add_f32_e32 v138, v142, v138
	v_add_f32_e32 v130, v134, v130
	v_add_f32_e32 v130, v138, v130
	v_fmamk_f32 v130, v130, 0x3a800000, v212
	v_rsq_f32_e32 v149, v130
	s_waitcnt vmcnt(3)
	v_add_f32_e32 v236, v236, v237
	s_waitcnt vmcnt(2)
	v_add_f32_e32 v240, v240, v241
	s_waitcnt vmcnt(1)
	v_add_f32_e32 v244, v244, v245
	s_waitcnt vmcnt(0)
	v_add_f32_e32 v248, v248, v249
	v_add_f32_e32 v249, v250, v251
	v_add_f32_e32 v245, v246, v247
	v_add_f32_e32 v241, v242, v243
	v_add_f32_e32 v237, v238, v239
	v_add_f32_e32 v248, v248, v249
	v_add_f32_e32 v244, v244, v245
	v_add_f32_e32 v240, v240, v241
	v_add_f32_e32 v236, v236, v237
	v_add_f32_e32 v244, v248, v244
	v_add_f32_e32 v236, v240, v236
	v_add_f32_e32 v236, v244, v236
	v_fmamk_f32 v236, v236, 0x3a800000, v212
	v_rsq_f32_e32 v236, v236
	v_lshl_add_u64 v[134:135], v[178:179], 2, s[44:45]
	s_add_u32 s44, s50, 0x800000
	s_addc_u32 s45, s51, 0
	ds_write2st64_b32 v150, v149, v236 offset1:1
	v_lshl_add_u32 v130, v146, 2, v147
	ds_read2_b32 v[196:197], v130 offset1:16
	ds_read2_b32 v[192:193], v130 offset0:32 offset1:48
	ds_read2_b32 v[188:189], v130 offset0:64 offset1:80
	ds_read2_b32 v[180:181], v130 offset0:96 offset1:112
	global_load_dwordx4 v[138:141], v[134:135], off offset:16
	global_load_dwordx4 v[142:145], v[134:135], off
	global_load_dwordx4 v[130:133], v[134:135], off offset:528
	s_nop 0
	global_load_dwordx4 v[134:137], v[134:135], off offset:512
	s_and_b64 s[42:43], s[46:47], s[42:43]
	s_and_b64 s[48:49], s[48:49], s[42:43]
	v_cndmask_b32_e64 v146, 0, 1, s[48:49]
	s_waitcnt lgkmcnt(3)
	v_mov_b32_e32 v194, v197
	s_waitcnt lgkmcnt(2)
	v_mov_b32_e32 v190, v193
	s_waitcnt lgkmcnt(1)
	v_mov_b32_e32 v186, v189
	s_waitcnt lgkmcnt(0)
	v_mov_b32_e32 v176, v181
	v_cmp_ne_u32_e64 s[42:43], 1, v146
	s_andn2_b64 vcc, exec, s[48:49]
	s_cbranch_vccnz .LBB0_610
	v_lshlrev_b64 v[146:147], 6, v[182:183]
	v_lshl_add_u64 v[158:159], s[44:45], 0, v[146:147]
	global_load_dwordx4 v[146:149], v[158:159], off offset:48
	global_load_dwordx4 v[154:157], v[158:159], off offset:32
	global_load_dwordx4 v[150:153], v[158:159], off offset:16
	s_nop 0
	global_load_dwordx4 v[158:161], v[158:159], off
	s_branch .LBB0_611

; #define LAS __attribute__((address_space(3)))
; DI float sum4(const float* p) { const f32x4 a = *(const f32x4*)p; return (a[0] + a[1]) + (a[2] + a[3]); }
; #define PK8(v0, v1) ((u32x4){pk2((v0)[0], (v0)[1]), pk2((v0)[2], (v0)[3]), pk2((v1)[0], (v1)[1]), pk2((v1)[2], (v1)[3])})
;     template <int NS> DI void rowstat(float (&rs)[2][4], const float* parts, float inv_n, float mul, int rowbase_wave, LAS float* buf, int lane, int fr) const {
; #pragma unroll
;         for (int h = 0; h < 2; ++h) { const float* pp = parts + (size_t)(rowbase_wave + h * 128 + lane) * (NS == 4 ? 4 : 16);
;             const float sm = NS == 16 ? sum16(pp) : (NS == 12 ? sum12(pp) : sum4(pp)); buf[h * 64 + lane] = __builtin_amdgcn_rsqf(sm * inv_n + EPS) * mul; }
; #pragma unroll
;         for (int ai = 0; ai < 2; ++ai)
; #pragma unroll
;             for (int m = 0; m < 4; ++m) rs[ai][m] = buf[ai * 64 + m * 16 + fr];
;     }
;     DI void operator()(const f32x4 (&acc)[2][2][4][2], const Unit& u, int wr, int wc, int fr, int fq, int tid, LAS unsigned char* lds) const {
;     ...
;         case K_KPE: { EPI_CASE_BEGIN
;             if (wc == 0) {
;                 bf16_t* dst = (bf16_t*)(ws + WS_KPE); const float* rt = (const float*)(ws + WS_ROPEM);
;                 rowstat<16>(rs, ssq1, 1.f / 1024.f, 1.f, rbw, rsbuf, lane, fr);
;                 const f32x4 b0 = *(const f32x4*)(bias1 + bidx * NWIN + 1024 + fq * 8), b1 = *(const f32x4*)(bias1 + bidx * NWIN + 1024 + fq * 8 + 4);
; #pragma unroll
;                 for (int ai = 0; ai < 2; ++ai)
; #pragma unroll
;                     for (int m = 0; m < 4; ++m) { const int row = row0 + ai * 128 + m * 16;
;                         const float* rr = rt + (size_t)row * 32 + (fq & 1) * 8;
;                         const f32x4 cs0 = *(const f32x4*)rr, cs1 = *(const f32x4*)(rr + 4), sn0 = *(const f32x4*)(rr + 16), sn1 = *(const f32x4*)(rr + 20);
;                         const f32x4 v0 = acc[ai][0][m][0] * rs[ai][m] + b0, v1 = acc[ai][0][m][1] * rs[ai][m] + b1; f32x4 p0, p1;
; #pragma unroll
;                         for (int e = 0; e < 4; ++e) { p0[e] = __shfl_xor(v0[e], 32); p1[e] = __shfl_xor(v1[e], 32); }
;                         const f32x4 o0 = fq < 2 ? (v0 * cs0 - p0 * sn0) : (p0 * sn0 + v0 * cs0), o1 = fq < 2 ? (v1 * cs1 - p1 * sn1) : (p1 * sn1 + v1 * cs1);
;                         *(u32x4*)(dst + (size_t)row * 32 + fq * 8) = PK8(o0, o1); }
.LBB0_794:
	s_andn2_b64 vcc, exec, s[42:43]
	s_cbranch_vccnz .LBB0_842
	s_cmp_gt_i32 s55, 1
	s_mov_b64 s[42:43], -1
	s_cbranch_scc0 .LBB0_799
	v_readlane_b32 s42, v252, 46
	v_readlane_b32 s43, v252, 47
	s_waitcnt vmcnt(0)
	v_mov_b32_e32 v140, v229
	s_waitcnt lgkmcnt(0)
	v_mov_b32_e32 v0, v230
	v_mov_b32_e32 v130, v231
	s_andn2_b64 vcc, exec, s[42:43]
	s_cbranch_vccnz .LBB0_798
	v_lshlrev_b32_e32 v131, 3, v130
	v_and_b32_e32 v130, 63, v130
	v_and_b32_e32 v131, 0xfffffe00, v131
	v_readlane_b32 s2, v252, 1
	v_or_b32_e32 v150, s54, v130
	v_ashrrev_i32_e32 v151, 31, v150
	v_add_u32_e32 v139, s2, v131
	v_lshl_add_u32 v141, v130, 2, v139
	v_lshlrev_b64 v[130:131], 6, v[150:151]
	v_lshl_add_u64 v[146:147], s[18:19], 0, v[130:131]
	global_load_dwordx4 v[130:133], v[146:147], off offset:48
	global_load_dwordx4 v[134:137], v[146:147], off offset:32
	global_load_dwordx4 v[142:145], v[146:147], off offset:16
	s_nop 0
	global_load_dwordx4 v[146:149], v[146:147], off
	v_add_u32_e32 v236, 0x80, v150
	v_ashrrev_i32_e32 v237, 31, v236
	v_lshlrev_b64 v[236:237], 6, v[236:237]
	v_lshl_add_u64 v[248:249], s[18:19], 0, v[236:237]
	global_load_dwordx4 v[236:239], v[248:249], off offset:48
	global_load_dwordx4 v[240:243], v[248:249], off offset:32
	global_load_dwordx4 v[244:247], v[248:249], off offset:16
	s_nop 0
	global_load_dwordx4 v[248:251], v[248:249], off
	s_mul_i32 s42, s14, 0x1d00
	s_ashr_i32 s43, s42, 31
	s_lshl_b64 s[42:43], s[42:43], 2
	v_lshlrev_b32_e32 v138, 3, v140
	s_add_u32 s42, s57, s42
	s_addc_u32 s43, s86, s43
	s_movk_i32 s2, 0x1000
	v_add_u32_e32 v160, s54, v0
	v_ashrrev_i32_e32 v161, 31, v160
	s_waitcnt vmcnt(7)
	v_add_f32_e32 v130, v130, v131
	s_waitcnt vmcnt(6)
	v_add_f32_e32 v134, v134, v135
	s_waitcnt vmcnt(5)
	v_add_f32_e32 v142, v142, v143
	s_waitcnt vmcnt(4)
	v_add_f32_e32 v146, v146, v147
	v_add_f32_e32 v147, v148, v149
	v_add_f32_e32 v143, v144, v145
	v_add_f32_e32 v135, v136, v137
	v_add_f32_e32 v131, v132, v133
	v_add_f32_e32 v146, v146, v147
	v_add_f32_e32 v142, v142, v143
	v_add_f32_e32 v134, v134, v135
	v_add_f32_e32 v130, v130, v131
	v_add_f32_e32 v142, v146, v142
	v_add_f32_e32 v130, v134, v130
	v_add_f32_e32 v130, v142, v130
	v_fmamk_f32 v130, v130, 0x3a800000, v212
	v_rsq_f32_e32 v151, v130
	s_waitcnt vmcnt(3)
	v_add_f32_e32 v236, v236, v237
	s_waitcnt vmcnt(2)
	v_add_f32_e32 v240, v240, v241
	s_waitcnt vmcnt(1)
	v_add_f32_e32 v244, v244, v245
	s_waitcnt vmcnt(0)
	v_add_f32_e32 v248, v248, v249
	v_add_f32_e32 v249, v250, v251
	v_add_f32_e32 v245, v246, v247
	v_add_f32_e32 v241, v242, v243
	v_add_f32_e32 v237, v238, v239
	v_add_f32_e32 v248, v248, v249
	v_add_f32_e32 v244, v244, v245
	v_add_f32_e32 v240, v240, v241
	v_add_f32_e32 v236, v236, v237
	v_add_f32_e32 v244, v248, v244
	v_add_f32_e32 v236, v240, v236
	v_add_f32_e32 v236, v244, v236
	v_fmamk_f32 v236, v236, 0x3a800000, v212
	v_rsq_f32_e32 v236, v236
	ds_write2st64_b32 v141, v151, v236 offset1:1
	v_lshl_add_u32 v130, v0, 2, v139
	v_ashrrev_i32_e32 v139, 31, v138
	ds_read2_b32 v[166:167], v130 offset1:16
	ds_read2_b32 v[164:165], v130 offset0:32 offset1:48
	ds_read2_b32 v[162:163], v130 offset0:64 offset1:80
	ds_read2_b32 v[156:157], v130 offset0:96 offset1:112
	v_lshl_add_u64 v[130:131], v[138:139], 2, s[42:43]
	s_mov_b64 s[42:43], 0x1000
	v_lshl_add_u64 v[134:135], v[130:131], 0, s[42:43]
	v_add_co_u32_e32 v130, vcc, s2, v130
	v_lshlrev_b32_e32 v0, 5, v140
	s_nop 0
	v_addc_co_u32_e32 v131, vcc, 0, v131, vcc
	global_load_dwordx4 v[130:133], v[130:131], off
	s_nop 0
	global_load_dwordx4 v[134:137], v[134:135], off offset:16
	v_and_b32_e32 v0, 32, v0
	v_lshl_add_u64 v[142:143], s[50:51], 0, v[0:1]
	s_mov_b64 s[42:43], 0x400000
	v_lshl_add_u64 v[158:159], v[142:143], 0, s[42:43]
	v_and_b32_e32 v141, 64, v216
	v_lshl_add_u64 v[138:139], v[138:139], 1, s[50:51]
	s_mov_b64 s[42:43], 0xb800000
	v_xor_b32_e32 v0, 32, v216
	v_add_u32_e32 v141, 64, v141
	v_lshl_add_u64 v[154:155], v[138:139], 0, s[42:43]
	v_lshlrev_b64 v[138:139], 7, v[160:161]
	v_cmp_lt_i32_e32 vcc, v0, v141
	v_lshl_add_u64 v[150:151], v[158:159], 0, v[138:139]
	s_waitcnt vmcnt(1) lgkmcnt(3)
	v_pk_fma_f32 v[176:177], v[128:129], v[166:167], v[132:133] op_sel_hi:[1,0,1]
	v_cndmask_b32_e32 v0, v216, v0, vcc
	v_cmp_gt_i32_e32 vcc, 2, v140
	global_load_dwordx4 v[138:141], v[150:151], off offset:16
	global_load_dwordx4 v[146:149], v[150:151], off
	global_load_dwordx4 v[142:145], v[150:151], off offset:80
	s_nop 0
	global_load_dwordx4 v[150:153], v[150:151], off offset:64
	v_lshlrev_b32_e32 v0, 2, v0
	v_pk_fma_f32 v[178:179], v[126:127], v[166:167], v[130:131] op_sel_hi:[1,0,1]
	ds_bpermute_b32 v184, v0, v178
	ds_bpermute_b32 v185, v0, v179
	ds_bpermute_b32 v188, v0, v176
	ds_bpermute_b32 v189, v0, v177
	s_waitcnt vmcnt(4)
	v_pk_fma_f32 v[180:181], v[124:125], v[166:167], v[136:137] op_sel_hi:[1,0,1]
	v_pk_fma_f32 v[182:183], v[122:123], v[166:167], v[134:135] op_sel_hi:[1,0,1]
	ds_bpermute_b32 v186, v0, v182
	ds_bpermute_b32 v187, v0, v183
	ds_bpermute_b32 v190, v0, v180
	ds_bpermute_b32 v191, v0, v181
	s_waitcnt vmcnt(1) lgkmcnt(0)
	v_pk_mul_f32 v[144:145], v[144:145], v[190:191]
	s_waitcnt vmcnt(0)
; #define PK8(v0, v1) ((u32x4){pk2((v0)[0], (v0)[1]), pk2((v0)[2], (v0)[3]), pk2((v1)[0], (v1)[1]), pk2((v1)[2], (v1)[3])})
;     DI void operator()(const f32x4 (&acc)[2][2][4][2], const Unit& u, int wr, int wc, int fr, int fq, int tid, LAS unsigned char* lds) const {
;     ...
;                     for (int m = 0; m < 4; ++m) { const int row = row0 + ai * 128 + m * 16;
;                         const float* rr = rt + (size_t)row * 32 + (fq & 1) * 8;
;                         const f32x4 cs0 = *(const f32x4*)rr, cs1 = *(const f32x4*)(rr + 4), sn0 = *(const f32x4*)(rr + 16), sn1 = *(const f32x4*)(rr + 20);
;                         const f32x4 v0 = acc[ai][0][m][0] * rs[ai][m] + b0, v1 = acc[ai][0][m][1] * rs[ai][m] + b1; f32x4 p0, p1;
; #pragma unroll
;                         for (int e = 0; e < 4; ++e) { p0[e] = __shfl_xor(v0[e], 32); p1[e] = __shfl_xor(v1[e], 32); }
;                         const f32x4 o0 = fq < 2 ? (v0 * cs0 - p0 * sn0) : (p0 * sn0 + v0 * cs0), o1 = fq < 2 ? (v1 * cs1 - p1 * sn1) : (p1 * sn1 + v1 * cs1);
;                         *(u32x4*)(dst + (size_t)row * 32 + fq * 8) = PK8(o0, o1); }
	v_pk_mul_f32 v[152:153], v[152:153], v[188:189]
	v_pk_mul_f32 v[150:151], v[150:151], v[184:185]
	v_xor_b32_e32 v166, 0x80000000, v152
	v_xor_b32_e32 v184, 0x80000000, v153
	v_xor_b32_e32 v185, 0x80000000, v150
	v_xor_b32_e32 v188, 0x80000000, v151
	v_cndmask_b32_e32 v153, v153, v184, vcc
	v_cndmask_b32_e32 v152, v152, v166, vcc
	v_cndmask_b32_e32 v151, v151, v188, vcc
	v_cndmask_b32_e32 v150, v150, v185, vcc
	v_pk_mul_f32 v[142:143], v[142:143], v[186:187]
	v_pk_fma_f32 v[148:149], v[176:177], v[148:149], v[152:153]
	v_pk_fma_f32 v[146:147], v[178:179], v[146:147], v[150:151]
	v_xor_b32_e32 v150, 0x80000000, v144
	v_xor_b32_e32 v151, 0x80000000, v145
	v_xor_b32_e32 v152, 0x80000000, v142
	v_xor_b32_e32 v153, 0x80000000, v143
	v_cndmask_b32_e32 v145, v145, v151, vcc
	v_cndmask_b32_e32 v144, v144, v150, vcc
	v_cndmask_b32_e32 v143, v143, v153, vcc
	v_cndmask_b32_e32 v142, v142, v152, vcc
	v_pk_fma_f32 v[144:145], v[180:181], v[140:141], v[144:145]
	v_pk_fma_f32 v[140:141], v[182:183], v[138:139], v[142:143]
	v_lshlrev_b64 v[142:143], 6, v[160:161]
	v_add_u32_e32 v176, 16, v160
	v_cvt_pk_bf16_f32 v138, v146, v147
	v_cvt_pk_bf16_f32 v139, v148, v149
	v_cvt_pk_bf16_f32 v140, v140, v141
	v_cvt_pk_bf16_f32 v141, v144, v145
	v_lshl_add_u64 v[142:143], v[154:155], 0, v[142:143]
	v_ashrrev_i32_e32 v177, 31, v176
	global_store_dwordx4 v[142:143], v[138:141], off
	v_mov_b32_e32 v166, v167
	v_pk_fma_f32 v[178:179], v[112:113], v[166:167], v[132:133] op_sel_hi:[1,0,1]
	v_lshlrev_b64 v[138:139], 7, v[176:177]
	v_lshl_add_u64 v[150:151], v[158:159], 0, v[138:139]
	global_load_dwordx4 v[138:141], v[150:151], off offset:16
	global_load_dwordx4 v[142:145], v[150:151], off
	global_load_dwordx4 v[146:149], v[150:151], off offset:80
	s_nop 0
	global_load_dwordx4 v[150:153], v[150:151], off offset:64
	v_pk_fma_f32 v[180:181], v[110:111], v[166:167], v[130:131] op_sel_hi:[1,0,1]
	ds_bpermute_b32 v184, v0, v180
	ds_bpermute_b32 v185, v0, v181
	ds_bpermute_b32 v188, v0, v178
	ds_bpermute_b32 v189, v0, v179
	v_pk_fma_f32 v[182:183], v[108:109], v[166:167], v[136:137] op_sel_hi:[1,0,1]
	v_pk_fma_f32 v[166:167], v[106:107], v[166:167], v[134:135] op_sel_hi:[1,0,1]
	ds_bpermute_b32 v186, v0, v166
	ds_bpermute_b32 v187, v0, v167
	ds_bpermute_b32 v190, v0, v182
	ds_bpermute_b32 v191, v0, v183
	s_waitcnt vmcnt(1) lgkmcnt(0)
	v_pk_mul_f32 v[148:149], v[148:149], v[190:191]
	s_waitcnt vmcnt(0)
	v_pk_mul_f32 v[152:153], v[152:153], v[188:189]
	v_pk_mul_f32 v[150:151], v[150:151], v[184:185]
	v_xor_b32_e32 v161, 0x80000000, v152
	v_xor_b32_e32 v184, 0x80000000, v153
	v_xor_b32_e32 v185, 0x80000000, v150
	v_xor_b32_e32 v188, 0x80000000, v151
	v_cndmask_b32_e32 v153, v153, v184, vcc
	v_cndmask_b32_e32 v152, v152, v161, vcc
	v_cndmask_b32_e32 v151, v151, v188, vcc
	v_cndmask_b32_e32 v150, v150, v185, vcc
	v_pk_mul_f32 v[146:147], v[146:147], v[186:187]
	v_pk_fma_f32 v[144:145], v[178:179], v[144:145], v[152:153]
	v_pk_fma_f32 v[142:143], v[180:181], v[142:143], v[150:151]
	v_xor_b32_e32 v150, 0x80000000, v148
	v_xor_b32_e32 v151, 0x80000000, v149
	v_xor_b32_e32 v152, 0x80000000, v146
	v_xor_b32_e32 v153, 0x80000000, v147
	v_cndmask_b32_e32 v149, v149, v151, vcc
	v_cndmask_b32_e32 v148, v148, v150, vcc
	v_cndmask_b32_e32 v147, v147, v153, vcc
	v_cndmask_b32_e32 v146, v146, v152, vcc
	v_pk_fma_f32 v[148:149], v[182:183], v[140:141], v[148:149]
	v_pk_fma_f32 v[140:141], v[166:167], v[138:139], v[146:147]
	v_cvt_pk_bf16_f32 v138, v142, v143
	v_lshlrev_b64 v[142:143], 6, v[176:177]
	v_add_u32_e32 v166, 32, v160
	v_cvt_pk_bf16_f32 v139, v144, v145
	v_cvt_pk_bf16_f32 v140, v140, v141
	v_cvt_pk_bf16_f32 v141, v148, v149
	v_lshl_add_u64 v[142:143], v[154:155], 0, v[142:143]
	v_ashrrev_i32_e32 v167, 31, v166
	global_store_dwordx4 v[142:143], v[138:141], off
	v_pk_fma_f32 v[176:177], v[96:97], v[164:165], v[132:133] op_sel_hi:[1,0,1]
	v_pk_fma_f32 v[178:179], v[94:95], v[164:165], v[130:131] op_sel_hi:[1,0,1]
	v_lshlrev_b64 v[138:139], 7, v[166:167]
	v_lshl_add_u64 v[150:151], v[158:159], 0, v[138:139]
	global_load_dwordx4 v[138:141], v[150:151], off offset:16
	global_load_dwordx4 v[142:145], v[150:151], off
	global_load_dwordx4 v[146:149], v[150:151], off offset:80
	s_nop 0
	global_load_dwordx4 v[150:153], v[150:151], off offset:64
	ds_bpermute_b32 v184, v0, v178
	ds_bpermute_b32 v185, v0, v179
	ds_bpermute_b32 v188, v0, v176
	ds_bpermute_b32 v189, v0, v177
	v_pk_fma_f32 v[180:181], v[92:93], v[164:165], v[136:137] op_sel_hi:[1,0,1]
	v_pk_fma_f32 v[182:183], v[90:91], v[164:165], v[134:135] op_sel_hi:[1,0,1]
	ds_bpermute_b32 v186, v0, v182
	ds_bpermute_b32 v187, v0, v183
	ds_bpermute_b32 v190, v0, v180
	ds_bpermute_b32 v191, v0, v181
	s_waitcnt vmcnt(1) lgkmcnt(0)
	v_pk_mul_f32 v[148:149], v[148:149], v[190:191]
	s_waitcnt vmcnt(0)
; #define PK8(v0, v1) ((u32x4){pk2((v0)[0], (v0)[1]), pk2((v0)[2], (v0)[3]), pk2((v1)[0], (v1)[1]), pk2((v1)[2], (v1)[3])})
;     DI void operator()(const f32x4 (&acc)[2][2][4][2], const Unit& u, int wr, int wc, int fr, int fq, int tid, LAS unsigned char* lds) const {
;     ...
;                     for (int m = 0; m < 4; ++m) { const int row = row0 + ai * 128 + m * 16;
;                         const float* rr = rt + (size_t)row * 32 + (fq & 1) * 8;
;                         const f32x4 cs0 = *(const f32x4*)rr, cs1 = *(const f32x4*)(rr + 4), sn0 = *(const f32x4*)(rr + 16), sn1 = *(const f32x4*)(rr + 20);
;                         const f32x4 v0 = acc[ai][0][m][0] * rs[ai][m] + b0, v1 = acc[ai][0][m][1] * rs[ai][m] + b1; f32x4 p0, p1;
; #pragma unroll
;                         for (int e = 0; e < 4; ++e) { p0[e] = __shfl_xor(v0[e], 32); p1[e] = __shfl_xor(v1[e], 32); }
;                         const f32x4 o0 = fq < 2 ? (v0 * cs0 - p0 * sn0) : (p0 * sn0 + v0 * cs0), o1 = fq < 2 ? (v1 * cs1 - p1 * sn1) : (p1 * sn1 + v1 * cs1);
;                         *(u32x4*)(dst + (size_t)row * 32 + fq * 8) = PK8(o0, o1); }
	v_pk_mul_f32 v[152:153], v[152:153], v[188:189]
	v_pk_mul_f32 v[150:151], v[150:151], v[184:185]
	v_xor_b32_e32 v161, 0x80000000, v152
	v_xor_b32_e32 v164, 0x80000000, v153
	v_xor_b32_e32 v184, 0x80000000, v150
	v_xor_b32_e32 v185, 0x80000000, v151
	v_cndmask_b32_e32 v153, v153, v164, vcc
	v_cndmask_b32_e32 v152, v152, v161, vcc
	v_cndmask_b32_e32 v151, v151, v185, vcc
	v_cndmask_b32_e32 v150, v150, v184, vcc
	v_pk_mul_f32 v[146:147], v[146:147], v[186:187]
	v_pk_fma_f32 v[144:145], v[176:177], v[144:145], v[152:153]
	v_pk_fma_f32 v[142:143], v[178:179], v[142:143], v[150:151]
	v_xor_b32_e32 v150, 0x80000000, v148
	v_xor_b32_e32 v151, 0x80000000, v149
	v_xor_b32_e32 v152, 0x80000000, v146
	v_xor_b32_e32 v153, 0x80000000, v147
	v_cndmask_b32_e32 v149, v149, v151, vcc
	v_cndmask_b32_e32 v148, v148, v150, vcc
	v_cndmask_b32_e32 v147, v147, v153, vcc
	v_cndmask_b32_e32 v146, v146, v152, vcc
	v_pk_fma_f32 v[148:149], v[180:181], v[140:141], v[148:149]
	v_pk_fma_f32 v[140:141], v[182:183], v[138:139], v[146:147]
	v_cvt_pk_bf16_f32 v138, v142, v143
	v_lshlrev_b64 v[142:143], 6, v[166:167]
	v_add_u32_e32 v166, 48, v160
	v_cvt_pk_bf16_f32 v139, v144, v145
	v_cvt_pk_bf16_f32 v140, v140, v141
	v_cvt_pk_bf16_f32 v141, v148, v149
	v_lshl_add_u64 v[142:143], v[154:155], 0, v[142:143]
	v_ashrrev_i32_e32 v167, 31, v166
	global_store_dwordx4 v[142:143], v[138:141], off
	v_mov_b32_e32 v164, v165
	v_pk_fma_f32 v[176:177], v[80:81], v[164:165], v[132:133] op_sel_hi:[1,0,1]
	v_lshlrev_b64 v[138:139], 7, v[166:167]
	v_lshl_add_u64 v[150:151], v[158:159], 0, v[138:139]
	global_load_dwordx4 v[138:141], v[150:151], off offset:16
	global_load_dwordx4 v[142:145], v[150:151], off
	global_load_dwordx4 v[146:149], v[150:151], off offset:80
	s_nop 0
	global_load_dwordx4 v[150:153], v[150:151], off offset:64
	v_pk_fma_f32 v[178:179], v[78:79], v[164:165], v[130:131] op_sel_hi:[1,0,1]
	ds_bpermute_b32 v182, v0, v178
	ds_bpermute_b32 v183, v0, v179
	ds_bpermute_b32 v186, v0, v176
	ds_bpermute_b32 v187, v0, v177
	v_pk_fma_f32 v[180:181], v[76:77], v[164:165], v[136:137] op_sel_hi:[1,0,1]
	v_pk_fma_f32 v[164:165], v[74:75], v[164:165], v[134:135] op_sel_hi:[1,0,1]
	ds_bpermute_b32 v184, v0, v164
	ds_bpermute_b32 v185, v0, v165
	ds_bpermute_b32 v188, v0, v180
	ds_bpermute_b32 v189, v0, v181
	s_waitcnt vmcnt(1) lgkmcnt(0)
	v_pk_mul_f32 v[148:149], v[148:149], v[188:189]
	s_waitcnt vmcnt(0)
	v_pk_mul_f32 v[152:153], v[152:153], v[186:187]
	v_pk_mul_f32 v[150:151], v[150:151], v[182:183]
	v_xor_b32_e32 v161, 0x80000000, v152
	v_xor_b32_e32 v182, 0x80000000, v153
	v_xor_b32_e32 v183, 0x80000000, v150
	v_xor_b32_e32 v186, 0x80000000, v151
	v_cndmask_b32_e32 v153, v153, v182, vcc
	v_cndmask_b32_e32 v152, v152, v161, vcc
	v_cndmask_b32_e32 v151, v151, v186, vcc
	v_cndmask_b32_e32 v150, v150, v183, vcc
	v_pk_mul_f32 v[146:147], v[146:147], v[184:185]
	v_pk_fma_f32 v[144:145], v[176:177], v[144:145], v[152:153]
	v_pk_fma_f32 v[142:143], v[178:179], v[142:143], v[150:151]
	v_xor_b32_e32 v150, 0x80000000, v148
	v_xor_b32_e32 v151, 0x80000000, v149
	v_xor_b32_e32 v152, 0x80000000, v146
	v_xor_b32_e32 v153, 0x80000000, v147
	v_cndmask_b32_e32 v149, v149, v151, vcc
	v_cndmask_b32_e32 v148, v148, v150, vcc
	v_cndmask_b32_e32 v147, v147, v153, vcc
	v_cndmask_b32_e32 v146, v146, v152, vcc
	v_pk_fma_f32 v[148:149], v[180:181], v[140:141], v[148:149]
	v_pk_fma_f32 v[140:141], v[164:165], v[138:139], v[146:147]
	v_cvt_pk_bf16_f32 v138, v142, v143
	v_lshlrev_b64 v[142:143], 6, v[166:167]
	v_add_u32_e32 v164, 0x80, v160
	v_cvt_pk_bf16_f32 v139, v144, v145
	v_cvt_pk_bf16_f32 v140, v140, v141
	v_cvt_pk_bf16_f32 v141, v148, v149
	v_lshl_add_u64 v[142:143], v[154:155], 0, v[142:143]
	v_ashrrev_i32_e32 v165, 31, v164
	global_store_dwordx4 v[142:143], v[138:141], off
	v_pk_fma_f32 v[166:167], v[64:65], v[162:163], v[132:133] op_sel_hi:[1,0,1]
	v_pk_fma_f32 v[176:177], v[62:63], v[162:163], v[130:131] op_sel_hi:[1,0,1]
	v_lshlrev_b64 v[138:139], 7, v[164:165]
	v_lshl_add_u64 v[150:151], v[158:159], 0, v[138:139]
	global_load_dwordx4 v[138:141], v[150:151], off offset:16
	global_load_dwordx4 v[142:145], v[150:151], off
	global_load_dwordx4 v[146:149], v[150:151], off offset:80
	s_nop 0
	global_load_dwordx4 v[150:153], v[150:151], off offset:64
	ds_bpermute_b32 v182, v0, v176
	ds_bpermute_b32 v183, v0, v177
	ds_bpermute_b32 v186, v0, v166
	ds_bpermute_b32 v187, v0, v167
	v_pk_fma_f32 v[178:179], v[60:61], v[162:163], v[136:137] op_sel_hi:[1,0,1]
	v_pk_fma_f32 v[180:181], v[58:59], v[162:163], v[134:135] op_sel_hi:[1,0,1]
	ds_bpermute_b32 v184, v0, v180
	ds_bpermute_b32 v185, v0, v181
	ds_bpermute_b32 v188, v0, v178
	ds_bpermute_b32 v189, v0, v179
	s_waitcnt vmcnt(1) lgkmcnt(0)
	v_pk_mul_f32 v[148:149], v[148:149], v[188:189]
	s_waitcnt vmcnt(0)
; #define PK8(v0, v1) ((u32x4){pk2((v0)[0], (v0)[1]), pk2((v0)[2], (v0)[3]), pk2((v1)[0], (v1)[1]), pk2((v1)[2], (v1)[3])})
;     DI void operator()(const f32x4 (&acc)[2][2][4][2], const Unit& u, int wr, int wc, int fr, int fq, int tid, LAS unsigned char* lds) const {
;     ...
;                     for (int m = 0; m < 4; ++m) { const int row = row0 + ai * 128 + m * 16;
;                         const float* rr = rt + (size_t)row * 32 + (fq & 1) * 8;
;                         const f32x4 cs0 = *(const f32x4*)rr, cs1 = *(const f32x4*)(rr + 4), sn0 = *(const f32x4*)(rr + 16), sn1 = *(const f32x4*)(rr + 20);
;                         const f32x4 v0 = acc[ai][0][m][0] * rs[ai][m] + b0, v1 = acc[ai][0][m][1] * rs[ai][m] + b1; f32x4 p0, p1;
; #pragma unroll
;                         for (int e = 0; e < 4; ++e) { p0[e] = __shfl_xor(v0[e], 32); p1[e] = __shfl_xor(v1[e], 32); }
;                         const f32x4 o0 = fq < 2 ? (v0 * cs0 - p0 * sn0) : (p0 * sn0 + v0 * cs0), o1 = fq < 2 ? (v1 * cs1 - p1 * sn1) : (p1 * sn1 + v1 * cs1);
;                         *(u32x4*)(dst + (size_t)row * 32 + fq * 8) = PK8(o0, o1); }
	v_pk_mul_f32 v[152:153], v[152:153], v[186:187]
	v_pk_mul_f32 v[150:151], v[150:151], v[182:183]
	v_xor_b32_e32 v161, 0x80000000, v152
	v_xor_b32_e32 v162, 0x80000000, v153
	v_xor_b32_e32 v182, 0x80000000, v150
	v_xor_b32_e32 v183, 0x80000000, v151
	v_cndmask_b32_e32 v153, v153, v162, vcc
	v_cndmask_b32_e32 v152, v152, v161, vcc
	v_cndmask_b32_e32 v151, v151, v183, vcc
	v_cndmask_b32_e32 v150, v150, v182, vcc
	v_pk_mul_f32 v[146:147], v[146:147], v[184:185]
	v_pk_fma_f32 v[144:145], v[166:167], v[144:145], v[152:153]
	v_pk_fma_f32 v[142:143], v[176:177], v[142:143], v[150:151]
	v_xor_b32_e32 v150, 0x80000000, v148
	v_xor_b32_e32 v151, 0x80000000, v149
	v_xor_b32_e32 v152, 0x80000000, v146
	v_xor_b32_e32 v153, 0x80000000, v147
	v_cndmask_b32_e32 v149, v149, v151, vcc
	v_cndmask_b32_e32 v148, v148, v150, vcc
	v_cndmask_b32_e32 v147, v147, v153, vcc
	v_cndmask_b32_e32 v146, v146, v152, vcc
	v_pk_fma_f32 v[148:149], v[178:179], v[140:141], v[148:149]
	v_pk_fma_f32 v[140:141], v[180:181], v[138:139], v[146:147]
	v_cvt_pk_bf16_f32 v138, v142, v143
	v_lshlrev_b64 v[142:143], 6, v[164:165]
	v_add_u32_e32 v164, 0x90, v160
	v_cvt_pk_bf16_f32 v139, v144, v145
	v_cvt_pk_bf16_f32 v140, v140, v141
	v_cvt_pk_bf16_f32 v141, v148, v149
	v_lshl_add_u64 v[142:143], v[154:155], 0, v[142:143]
	v_ashrrev_i32_e32 v165, 31, v164
	global_store_dwordx4 v[142:143], v[138:141], off
	v_mov_b32_e32 v162, v163
	v_pk_fma_f32 v[166:167], v[48:49], v[162:163], v[132:133] op_sel_hi:[1,0,1]
	v_lshlrev_b64 v[138:139], 7, v[164:165]
	v_lshl_add_u64 v[150:151], v[158:159], 0, v[138:139]
	global_load_dwordx4 v[138:141], v[150:151], off offset:16
	global_load_dwordx4 v[142:145], v[150:151], off
	global_load_dwordx4 v[146:149], v[150:151], off offset:80
	s_nop 0
	global_load_dwordx4 v[150:153], v[150:151], off offset:64
	v_pk_fma_f32 v[176:177], v[46:47], v[162:163], v[130:131] op_sel_hi:[1,0,1]
	ds_bpermute_b32 v180, v0, v176
	ds_bpermute_b32 v181, v0, v177
	ds_bpermute_b32 v184, v0, v166
	ds_bpermute_b32 v185, v0, v167
	v_pk_fma_f32 v[178:179], v[44:45], v[162:163], v[136:137] op_sel_hi:[1,0,1]
	v_pk_fma_f32 v[162:163], v[42:43], v[162:163], v[134:135] op_sel_hi:[1,0,1]
	ds_bpermute_b32 v182, v0, v162
	ds_bpermute_b32 v183, v0, v163
	ds_bpermute_b32 v186, v0, v178
	ds_bpermute_b32 v187, v0, v179
	s_waitcnt vmcnt(1) lgkmcnt(0)
	v_pk_mul_f32 v[148:149], v[148:149], v[186:187]
	s_waitcnt vmcnt(0)
	v_pk_mul_f32 v[152:153], v[152:153], v[184:185]
	v_pk_mul_f32 v[150:151], v[150:151], v[180:181]
	v_xor_b32_e32 v161, 0x80000000, v152
	v_xor_b32_e32 v180, 0x80000000, v153
	v_xor_b32_e32 v181, 0x80000000, v150
	v_xor_b32_e32 v184, 0x80000000, v151
	v_cndmask_b32_e32 v153, v153, v180, vcc
	v_cndmask_b32_e32 v152, v152, v161, vcc
	v_cndmask_b32_e32 v151, v151, v184, vcc
	v_cndmask_b32_e32 v150, v150, v181, vcc
	v_pk_mul_f32 v[146:147], v[146:147], v[182:183]
	v_pk_fma_f32 v[144:145], v[166:167], v[144:145], v[152:153]
	v_pk_fma_f32 v[142:143], v[176:177], v[142:143], v[150:151]
	v_xor_b32_e32 v150, 0x80000000, v148
	v_xor_b32_e32 v151, 0x80000000, v149
	v_xor_b32_e32 v152, 0x80000000, v146
	v_xor_b32_e32 v153, 0x80000000, v147
	v_cndmask_b32_e32 v149, v149, v151, vcc
	v_cndmask_b32_e32 v148, v148, v150, vcc
	v_cndmask_b32_e32 v147, v147, v153, vcc
	v_cndmask_b32_e32 v146, v146, v152, vcc
	v_pk_fma_f32 v[148:149], v[178:179], v[140:141], v[148:149]
	v_pk_fma_f32 v[140:141], v[162:163], v[138:139], v[146:147]
	v_cvt_pk_bf16_f32 v138, v142, v143
	v_lshlrev_b64 v[142:143], 6, v[164:165]
	v_add_u32_e32 v162, 0xa0, v160
	v_cvt_pk_bf16_f32 v139, v144, v145
	v_cvt_pk_bf16_f32 v140, v140, v141
	v_cvt_pk_bf16_f32 v141, v148, v149
	v_lshl_add_u64 v[142:143], v[154:155], 0, v[142:143]
	v_ashrrev_i32_e32 v163, 31, v162
	global_store_dwordx4 v[142:143], v[138:141], off
	v_pk_fma_f32 v[164:165], v[32:33], v[156:157], v[132:133] op_sel_hi:[1,0,1]
	v_pk_fma_f32 v[166:167], v[30:31], v[156:157], v[130:131] op_sel_hi:[1,0,1]
	v_lshlrev_b64 v[138:139], 7, v[162:163]
	v_lshl_add_u64 v[150:151], v[158:159], 0, v[138:139]
	global_load_dwordx4 v[138:141], v[150:151], off offset:16
	global_load_dwordx4 v[142:145], v[150:151], off
	global_load_dwordx4 v[146:149], v[150:151], off offset:80
	s_nop 0
	global_load_dwordx4 v[150:153], v[150:151], off offset:64
	ds_bpermute_b32 v180, v0, v166
	ds_bpermute_b32 v181, v0, v167
	ds_bpermute_b32 v184, v0, v164
	ds_bpermute_b32 v185, v0, v165
	v_pk_fma_f32 v[176:177], v[28:29], v[156:157], v[136:137] op_sel_hi:[1,0,1]
	v_pk_fma_f32 v[178:179], v[26:27], v[156:157], v[134:135] op_sel_hi:[1,0,1]
	ds_bpermute_b32 v182, v0, v178
	ds_bpermute_b32 v183, v0, v179
	ds_bpermute_b32 v186, v0, v176
	ds_bpermute_b32 v187, v0, v177
	s_waitcnt vmcnt(1) lgkmcnt(0)
; #define PK8(v0, v1) ((u32x4){pk2((v0)[0], (v0)[1]), pk2((v0)[2], (v0)[3]), pk2((v1)[0], (v1)[1]), pk2((v1)[2], (v1)[3])})
;     DI void operator()(const f32x4 (&acc)[2][2][4][2], const Unit& u, int wr, int wc, int fr, int fq, int tid, LAS unsigned char* lds) const {
;     ...
;                     for (int m = 0; m < 4; ++m) { const int row = row0 + ai * 128 + m * 16;
;                         const float* rr = rt + (size_t)row * 32 + (fq & 1) * 8;
;                         const f32x4 cs0 = *(const f32x4*)rr, cs1 = *(const f32x4*)(rr + 4), sn0 = *(const f32x4*)(rr + 16), sn1 = *(const f32x4*)(rr + 20);
;                         const f32x4 v0 = acc[ai][0][m][0] * rs[ai][m] + b0, v1 = acc[ai][0][m][1] * rs[ai][m] + b1; f32x4 p0, p1;
; #pragma unroll
;                         for (int e = 0; e < 4; ++e) { p0[e] = __shfl_xor(v0[e], 32); p1[e] = __shfl_xor(v1[e], 32); }
;                         const f32x4 o0 = fq < 2 ? (v0 * cs0 - p0 * sn0) : (p0 * sn0 + v0 * cs0), o1 = fq < 2 ? (v1 * cs1 - p1 * sn1) : (p1 * sn1 + v1 * cs1);
;                         *(u32x4*)(dst + (size_t)row * 32 + fq * 8) = PK8(o0, o1); }
	v_pk_mul_f32 v[148:149], v[148:149], v[186:187]
	s_waitcnt vmcnt(0)
	v_pk_mul_f32 v[152:153], v[152:153], v[184:185]
	v_pk_mul_f32 v[150:151], v[150:151], v[180:181]
	v_xor_b32_e32 v156, 0x80000000, v152
	v_xor_b32_e32 v161, 0x80000000, v153
	v_xor_b32_e32 v180, 0x80000000, v150
	v_xor_b32_e32 v181, 0x80000000, v151
	v_cndmask_b32_e32 v153, v153, v161, vcc
	v_cndmask_b32_e32 v152, v152, v156, vcc
	v_cndmask_b32_e32 v151, v151, v181, vcc
	v_cndmask_b32_e32 v150, v150, v180, vcc
	v_pk_mul_f32 v[146:147], v[146:147], v[182:183]
	v_pk_fma_f32 v[144:145], v[164:165], v[144:145], v[152:153]
	v_pk_fma_f32 v[142:143], v[166:167], v[142:143], v[150:151]
	v_xor_b32_e32 v150, 0x80000000, v148
	v_xor_b32_e32 v151, 0x80000000, v149
	v_xor_b32_e32 v152, 0x80000000, v146
	v_xor_b32_e32 v153, 0x80000000, v147
	v_cndmask_b32_e32 v149, v149, v151, vcc
	v_cndmask_b32_e32 v148, v148, v150, vcc
	v_cndmask_b32_e32 v147, v147, v153, vcc
	v_cndmask_b32_e32 v146, v146, v152, vcc
	v_pk_fma_f32 v[148:149], v[176:177], v[140:141], v[148:149]
	v_pk_fma_f32 v[140:141], v[178:179], v[138:139], v[146:147]
	v_cvt_pk_bf16_f32 v138, v142, v143
	v_lshlrev_b64 v[142:143], 6, v[162:163]
	v_cvt_pk_bf16_f32 v139, v144, v145
	v_cvt_pk_bf16_f32 v140, v140, v141
	v_cvt_pk_bf16_f32 v141, v148, v149
	v_lshl_add_u64 v[142:143], v[154:155], 0, v[142:143]
	global_store_dwordx4 v[142:143], v[138:141], off
	s_nop 1
	v_add_u32_e32 v138, 0xb0, v160
	v_ashrrev_i32_e32 v139, 31, v138
	v_lshlrev_b64 v[140:141], 7, v[138:139]
	v_lshl_add_u64 v[152:153], v[158:159], 0, v[140:141]
	global_load_dwordx4 v[140:143], v[152:153], off offset:16
	global_load_dwordx4 v[144:147], v[152:153], off
	global_load_dwordx4 v[148:151], v[152:153], off offset:80
	global_load_dwordx4 v[158:161], v[152:153], off offset:64
	v_mov_b32_e32 v152, v157
	v_pk_fma_f32 v[132:133], v[16:17], v[152:153], v[132:133] op_sel_hi:[1,0,1]
	v_pk_fma_f32 v[130:131], v[14:15], v[152:153], v[130:131] op_sel_hi:[1,0,1]
	ds_bpermute_b32 v162, v0, v132
	ds_bpermute_b32 v163, v0, v133
	v_pk_fma_f32 v[136:137], v[12:13], v[152:153], v[136:137] op_sel_hi:[1,0,1]
	v_pk_fma_f32 v[134:135], v[10:11], v[152:153], v[134:135] op_sel_hi:[1,0,1]
	ds_bpermute_b32 v152, v0, v130
	ds_bpermute_b32 v153, v0, v131
	ds_bpermute_b32 v156, v0, v134
	ds_bpermute_b32 v157, v0, v135
	ds_bpermute_b32 v164, v0, v136
	ds_bpermute_b32 v165, v0, v137
	s_waitcnt vmcnt(0) lgkmcnt(6)
	v_pk_mul_f32 v[160:161], v[160:161], v[162:163]
	s_waitcnt lgkmcnt(4)
	v_pk_mul_f32 v[152:153], v[158:159], v[152:153]
	v_xor_b32_e32 v0, 0x80000000, v160
	v_xor_b32_e32 v158, 0x80000000, v161
	v_xor_b32_e32 v162, 0x80000000, v152
	v_xor_b32_e32 v163, 0x80000000, v153
	v_cndmask_b32_e32 v159, v161, v158, vcc
	v_cndmask_b32_e32 v158, v160, v0, vcc
	v_cndmask_b32_e32 v153, v153, v163, vcc
	v_cndmask_b32_e32 v152, v152, v162, vcc
	v_pk_fma_f32 v[132:133], v[132:133], v[146:147], v[158:159]
	s_waitcnt lgkmcnt(2)
	v_pk_mul_f32 v[146:147], v[148:149], v[156:157]
	v_pk_fma_f32 v[130:131], v[130:131], v[144:145], v[152:153]
	s_waitcnt lgkmcnt(0)
	v_pk_mul_f32 v[144:145], v[150:151], v[164:165]
	v_xor_b32_e32 v149, 0x80000000, v146
	v_xor_b32_e32 v150, 0x80000000, v147
	v_xor_b32_e32 v0, 0x80000000, v144
	v_xor_b32_e32 v148, 0x80000000, v145
	v_cndmask_b32_e32 v147, v147, v150, vcc
	v_cndmask_b32_e32 v146, v146, v149, vcc
	v_cndmask_b32_e32 v145, v145, v148, vcc
	v_cndmask_b32_e32 v144, v144, v0, vcc
	v_pk_fma_f32 v[134:135], v[134:135], v[140:141], v[146:147]
	v_pk_fma_f32 v[136:137], v[136:137], v[142:143], v[144:145]
	v_cvt_pk_bf16_f32 v130, v130, v131
	v_cvt_pk_bf16_f32 v131, v132, v133
	v_cvt_pk_bf16_f32 v132, v134, v135
	v_lshlrev_b64 v[134:135], 6, v[138:139]
	v_cvt_pk_bf16_f32 v133, v136, v137
	v_lshl_add_u64 v[134:135], v[154:155], 0, v[134:135]
	global_store_dwordx4 v[134:135], v[130:133], off

; #define LAS __attribute__((address_space(3)))
; DI float sum4(const float* p) { const f32x4 a = *(const f32x4*)p; return (a[0] + a[1]) + (a[2] + a[3]); }
;     template <int NS> DI void rowstat(float (&rs)[2][4], const float* parts, float inv_n, float mul, int rowbase_wave, LAS float* buf, int lane, int fr) const {
; #pragma unroll
;         for (int h = 0; h < 2; ++h) { const float* pp = parts + (size_t)(rowbase_wave + h * 128 + lane) * (NS == 4 ? 4 : 16);
;             const float sm = NS == 16 ? sum16(pp) : (NS == 12 ? sum12(pp) : sum4(pp)); buf[h * 64 + lane] = __builtin_amdgcn_rsqf(sm * inv_n + EPS) * mul; }
; #pragma unroll
;         for (int ai = 0; ai < 2; ++ai)
; #pragma unroll
;             for (int m = 0; m < 4; ++m) rs[ai][m] = buf[ai * 64 + m * 16 + fr];
;     }
;     DI void operator()(const f32x4 (&acc)[2][2][4][2], const Unit& u, int wr, int wc, int fr, int fq, int tid, LAS unsigned char* lds) const {
;     ...
;         case K_QLAT: case K_CKV: { EPI_CASE_BEGIN
;             const bool isq = u.kind == K_QLAT;
;             bf16_t* dst = (bf16_t*)(ws + (isq ? WS_QLAT : WS_CKV)); const int ld = isq ? 768 : 256; const int cb = isq ? u.pn * 256 : 0;
;             float* ssq = (float*)(ws + (isq ? WS_SSQQP : WS_SSQKVP));
;             rowstat<16>(rs, ssq1, 1.f / 1024.f, 1.f, rbw, rsbuf, lane, fr);
;             f32x4 bv[2][2];
; #pragma unroll
;             for (int bj = 0; bj < 2; ++bj)
; #pragma unroll
;                 for (int n = 0; n < 2; ++n) bv[bj][n] = *(const f32x4*)(bias1 + bidx * NWIN + u.pn * 256 + lc0 + bj * 128 + n * 4);
; #pragma unroll
;             for (int ai = 0; ai < 2; ++ai)
; #pragma unroll
;                 for (int m = 0; m < 4; ++m) { const int row = row0 + ai * 128 + m * 16; float s = 0.f;
; #pragma unroll
;                     for (int bj = 0; bj < 2; ++bj) { const f32x4 v0 = acc[ai][bj][m][0] * rs[ai][m] + bv[bj][0], v1 = acc[ai][bj][m][1] * rs[ai][m] + bv[bj][1];
;                         s += ((v0[0] * v0[0] + v0[1] * v0[1]) + (v0[2] * v0[2] + v0[3] * v0[3])) + ((v1[0] * v1[0] + v1[1] * v1[1]) + (v1[2] * v1[2] + v1[3] * v1[3]));
;                         *(u32x4*)(dst + (size_t)row * ld + cb + lc0 + bj * 128) = PK8(v0, v1); }
;                     s += __shfl_xor(s, 16); s += __shfl_xor(s, 32);
;                     if (fq == 0) { if (isq) ssq[(size_t)row * 16 + u.pn * 4 + wc] = s; else ssq[(size_t)row * 4 + wc] = s; } }
.LBB0_799:
	s_andn2_b64 vcc, exec, s[42:43]
	s_cbranch_vccnz .LBB0_842
	s_cmp_lt_i32 s55, 0
	s_cbranch_scc1 .LBB0_842
	v_readlane_b32 s44, v252, 1
	s_waitcnt lgkmcnt(0)
	v_and_b32_e32 v0, 63, v231
	v_lshlrev_b32_e32 v130, 3, v231
	s_waitcnt vmcnt(0)
	v_or_b32_e32 v146, s54, v0
	v_and_b32_e32 v130, 0xfffffe00, v130
	v_ashrrev_i32_e32 v147, 31, v146
	v_add_u32_e32 v148, s44, v130
	v_lshlrev_b64 v[130:131], 6, v[146:147]
	v_lshl_add_u64 v[142:143], s[18:19], 0, v[130:131]
	global_load_dwordx4 v[130:133], v[142:143], off offset:48
	global_load_dwordx4 v[134:137], v[142:143], off offset:32
	global_load_dwordx4 v[138:141], v[142:143], off offset:16
	s_nop 0
	global_load_dwordx4 v[142:145], v[142:143], off
	v_add_u32_e32 v236, 0x80, v146
	v_ashrrev_i32_e32 v237, 31, v236
	v_lshlrev_b64 v[236:237], 6, v[236:237]
	v_lshl_add_u64 v[248:249], s[18:19], 0, v[236:237]
	global_load_dwordx4 v[236:239], v[248:249], off offset:48
	global_load_dwordx4 v[240:243], v[248:249], off offset:32
	global_load_dwordx4 v[244:247], v[248:249], off offset:16
	s_nop 0
	global_load_dwordx4 v[248:251], v[248:249], off
	s_lshl_b32 s46, s38, 8
	s_cmp_eq_u32 s55, 0
	s_movk_i32 s2, 0x300
	s_cselect_b32 s66, s2, 0x100
	s_mov_b32 s2, 0x1f200000
	s_cselect_b32 s49, s2, 0x1f400000
	s_ashr_i32 s47, s46, 31
	s_cmp_eq_u32 s55, 0
	s_mov_b32 s2, 0xa800000
	s_cselect_b32 s2, 0x7800000, s2
	s_cselect_b32 s42, s46, 0
	s_cselect_b32 s43, s47, 0
	s_cmp_lg_u32 s55, 0
	s_cselect_b64 s[44:45], -1, 0
	s_add_u32 s48, s50, s2
	s_addc_u32 s2, s51, 0
	v_lshl_add_u32 v152, v229, 3, s24
	v_lshl_add_u32 v0, v0, 2, v148
	v_ashrrev_i32_e32 v153, 31, v152
	v_add_u32_e32 v150, s54, v230
	v_and_b32_e32 v149, 64, v216
	v_add_u32_e32 v151, 64, v149
	s_waitcnt vmcnt(7)
	v_add_f32_e32 v130, v130, v131
	s_waitcnt vmcnt(6)
	v_add_f32_e32 v134, v134, v135
	s_waitcnt vmcnt(5)
	v_add_f32_e32 v138, v138, v139
	s_waitcnt vmcnt(4)
	v_add_f32_e32 v142, v142, v143
	v_add_f32_e32 v143, v144, v145
	v_add_f32_e32 v139, v140, v141
	v_add_f32_e32 v135, v136, v137
	v_add_f32_e32 v131, v132, v133
	v_add_f32_e32 v142, v142, v143
	v_add_f32_e32 v138, v138, v139
	v_add_f32_e32 v134, v134, v135
	v_add_f32_e32 v130, v130, v131
	v_add_f32_e32 v138, v142, v138
	v_add_f32_e32 v130, v134, v130
	v_add_f32_e32 v130, v138, v130
	v_fmamk_f32 v130, v130, 0x3a800000, v212
	v_rsq_f32_e32 v147, v130
	s_mul_i32 s18, s14, 0x1d00
	s_ashr_i32 s19, s18, 31
	s_lshl_b64 s[18:19], s[18:19], 2
	s_add_u32 s14, s57, s18
	s_addc_u32 s55, s86, s19
	s_lshl_b64 s[18:19], s[46:47], 2
	s_add_u32 s18, s14, s18
	s_addc_u32 s19, s55, s19
	s_waitcnt vmcnt(3)
	v_add_f32_e32 v236, v236, v237
	s_waitcnt vmcnt(2)
	v_add_f32_e32 v240, v240, v241
	s_waitcnt vmcnt(1)
	v_add_f32_e32 v244, v244, v245
	s_waitcnt vmcnt(0)
	v_add_f32_e32 v248, v248, v249
	v_add_f32_e32 v249, v250, v251
	v_add_f32_e32 v245, v246, v247
	v_add_f32_e32 v241, v242, v243
	v_add_f32_e32 v237, v238, v239
	v_add_f32_e32 v248, v248, v249
	v_add_f32_e32 v244, v244, v245
	v_add_f32_e32 v240, v240, v241
	v_add_f32_e32 v236, v236, v237
	v_add_f32_e32 v244, v248, v244
	v_add_f32_e32 v236, v240, v236
	v_add_f32_e32 v236, v244, v236
	v_fmamk_f32 v236, v236, 0x3a800000, v212
	v_rsq_f32_e32 v236, v236
	v_lshl_add_u64 v[134:135], v[152:153], 2, s[18:19]
	s_add_u32 s18, s50, s49
	s_addc_u32 s19, s51, 0
	ds_write2st64_b32 v0, v147, v236 offset1:1
	v_lshl_add_u32 v0, v230, 2, v148
	ds_read2_b32 v[162:163], v0 offset1:16
	ds_read2_b32 v[158:159], v0 offset0:32 offset1:48
	ds_read2_b32 v[154:155], v0 offset0:64 offset1:80
	ds_read2_b32 v[146:147], v0 offset0:96 offset1:112
	global_load_dwordx4 v[138:141], v[134:135], off offset:16
	global_load_dwordx4 v[142:145], v[134:135], off
	global_load_dwordx4 v[130:133], v[134:135], off offset:528
	s_nop 0
	global_load_dwordx4 v[134:137], v[134:135], off offset:512
	s_lshl_b64 s[42:43], s[42:43], 1
	s_add_u32 s42, s48, s42
	s_waitcnt lgkmcnt(1)
	v_mov_b32_e32 v148, v155
	s_addc_u32 s43, s2, s43
	v_lshl_add_u64 v[152:153], v[152:153], 1, s[42:43]
	v_mad_i64_i32 v[164:165], s[48:49], s66, v150, 0
	v_lshl_add_u64 v[164:165], v[164:165], 1, v[152:153]
	s_waitcnt lgkmcnt(0)
	v_mov_b32_e32 v0, v147
	v_xor_b32_e32 v147, 16, v216
	v_cmp_lt_i32_e32 vcc, v147, v151
	s_lshl_b32 s2, s13, 2
	s_add_u32 s46, s18, s2
	v_cndmask_b32_e32 v147, v216, v147, vcc
	v_lshlrev_b32_e32 v149, 2, v147
	v_xor_b32_e32 v147, 32, v216
	v_cmp_lt_i32_e32 vcc, v147, v151
	v_mov_b32_e32 v160, v163
	v_mov_b32_e32 v156, v159
	v_cndmask_b32_e32 v147, v216, v147, vcc
	v_lshlrev_b32_e32 v147, 2, v147
	v_cmp_eq_u32_e64 s[42:43], 0, v229
	s_addc_u32 s47, s19, 0
	v_ashrrev_i32_e32 v151, 31, v150
	s_waitcnt vmcnt(3)
	v_pk_fma_f32 v[166:167], v[124:125], v[162:163], v[140:141] op_sel_hi:[1,0,1]
	s_waitcnt vmcnt(2)
	v_pk_fma_f32 v[128:129], v[128:129], v[162:163], v[144:145] op_sel_hi:[1,0,1]
	v_pk_fma_f32 v[126:127], v[126:127], v[162:163], v[142:143] op_sel_hi:[1,0,1]
	v_pk_fma_f32 v[124:125], v[122:123], v[162:163], v[138:139] op_sel_hi:[1,0,1]
	v_mul_f32_e32 v122, v127, v127
	v_mul_f32_e32 v123, v129, v129
	v_fmac_f32_e32 v122, v126, v126
	v_fmac_f32_e32 v123, v128, v128
	v_add_f32_e32 v122, v122, v123
	v_mul_f32_e32 v123, v125, v125
	v_mul_f32_e32 v155, v167, v167
	v_fmac_f32_e32 v123, v124, v124
	v_fmac_f32_e32 v155, v166, v166
	v_add_f32_e32 v123, v123, v155
	v_add_f32_e32 v155, v122, v123
	v_cvt_pk_bf16_f32 v122, v126, v127
	v_cvt_pk_bf16_f32 v123, v128, v129
	v_cvt_pk_bf16_f32 v124, v124, v125
	v_cvt_pk_bf16_f32 v125, v166, v167
	s_waitcnt vmcnt(0)
	v_pk_fma_f32 v[120:121], v[120:121], v[162:163], v[136:137] op_sel_hi:[1,0,1]
	v_pk_fma_f32 v[118:119], v[118:119], v[162:163], v[134:135] op_sel_hi:[1,0,1]
	global_store_dwordx4 v[164:165], v[122:125], off
	s_nop 1
	v_pk_fma_f32 v[122:123], v[116:117], v[162:163], v[132:133] op_sel_hi:[1,0,1]
	v_pk_fma_f32 v[116:117], v[114:115], v[162:163], v[130:131] op_sel_hi:[1,0,1]
	v_mul_f32_e32 v114, v119, v119
	v_mul_f32_e32 v115, v121, v121
	v_fmac_f32_e32 v114, v118, v118
	v_fmac_f32_e32 v115, v120, v120
	v_add_f32_e32 v114, v114, v115
	v_mul_f32_e32 v115, v117, v117
	v_mul_f32_e32 v124, v123, v123
	v_fmac_f32_e32 v115, v116, v116
	v_fmac_f32_e32 v124, v122, v122
	v_add_f32_e32 v115, v115, v124
	v_add_f32_e32 v114, v114, v115
	v_add_f32_e32 v124, v155, v114
	v_cvt_pk_bf16_f32 v114, v118, v119
	v_cvt_pk_bf16_f32 v115, v120, v121
	v_cvt_pk_bf16_f32 v116, v116, v117
	v_cvt_pk_bf16_f32 v117, v122, v123
	global_store_dwordx4 v[164:165], v[114:117], off offset:256
	ds_bpermute_b32 v114, v149, v124
	s_waitcnt lgkmcnt(0)
	v_add_f32_e32 v114, v124, v114
	ds_bpermute_b32 v115, v147, v114
	s_and_saveexec_b64 s[48:49], s[42:43]
	s_cbranch_execz .LBB0_806
	s_waitcnt lgkmcnt(0)
	v_add_f32_e32 v114, v114, v115
	s_mov_b64 s[50:51], -1
	s_and_b64 vcc, exec, s[44:45]
	s_cbranch_vccz .LBB0_804
	v_lshl_add_u64 v[116:117], v[150:151], 4, s[46:47]
	global_store_dword v[116:117], v114, off
	s_mov_b64 s[50:51], 0
